# router: LDS fragment reads software-pipelined at half-chunk granularity (one barrier per chunk, reads overlap the dependent MFMA chain)
# baseline (speedup 1.0000x reference)
; __device__ __forceinline__ void phase_row1(const Frame& F, int l) {
;     ...
;         {
;             const int fr = lane & 15, fq = lane >> 4, tile = w >> 1, nt = w & 1;
;             const float* wp = (const float*)(F.ws + WS_RWT) + ((size_t)l * NE + 16 * nt + fr) * D + 256 * fq;
;             const float* hp = H32 + (size_t)(chunk * 64 + 16 * tile + fr) * D + 256 * fq;
;             f32x4 c = {0.f, 0.f, 0.f, 0.f};
; #pragma unroll 16
;             for (int s4 = 0; s4 < 256; s4 += 4) { const f32x4 a = *(const f32x4*)(wp + s4), bq = *(const f32x4*)(hp + s4);
;                 c = __builtin_amdgcn_mfma_f32_16x16x4f32(a.x, bq.x, c, 0, 0, 0); c = __builtin_amdgcn_mfma_f32_16x16x4f32(a.y, bq.y, c, 0, 0, 0);
;                 c = __builtin_amdgcn_mfma_f32_16x16x4f32(a.z, bq.z, c, 0, 0, 0); c = __builtin_amdgcn_mfma_f32_16x16x4f32(a.w, bq.w, c, 0, 0, 0); }
.LBB0_2151:
	v_readfirstlane_b32 s4, v0
	v_readfirstlane_b32 s5, v134
	v_and_b32_e32 v22, 63, v0
	v_lshrrev_b32_e32 v23, 5, v22
	s_lshr_b32 s6, s4, 7
	s_lshl_b32 s6, s6, 4
	s_sub_i32 s5, s5, s6
	s_lshr_b32 s6, s4, 3
	s_add_i32 s5, s5, s6
	v_add_u32_e32 v24, s5, v23
	v_mov_b32_e32 v25, 0
	v_lshlrev_b64 v[24:25], 12, v[24:25]
	v_lshl_add_u64 v[24:25], s[78:79], 0, v[24:25]
	v_lshlrev_b32_e32 v26, 7, v22
	v_and_b32_e32 v26, 0xc00, v26
	v_and_b32_e32 v27, 7, v22
	v_xor_b32_e32 v27, v27, v23
	v_lshlrev_b32_e32 v27, 4, v27
	v_mov_b32_e32 v29, 0
	s_mov_b32 s7, 0
	s_mov_b32 s6, 0x11000000
	v_xor_b32_e32 v28, 0, v27
	v_or_b32_e32 v28, v28, v26
	v_lshl_add_u64 v[30:31], v[24:25], 0, s[6:7]
	v_lshl_add_u64 v[30:31], v[30:31], 0, v[28:29]
	s_mov_b32 s6, 0x11002000
	v_xor_b32_e32 v28, 32, v27
	v_or_b32_e32 v28, v28, v26
	v_lshl_add_u64 v[32:33], v[24:25], 0, s[6:7]
	v_lshl_add_u64 v[32:33], v[32:33], 0, v[28:29]
	s_mov_b32 s6, 0x11004000
	v_xor_b32_e32 v28, 64, v27
	v_or_b32_e32 v28, v28, v26
	v_lshl_add_u64 v[34:35], v[24:25], 0, s[6:7]
	v_lshl_add_u64 v[34:35], v[34:35], 0, v[28:29]
	s_mov_b32 s6, 0x11006000
	v_xor_b32_e32 v28, 0x60, v27
	v_or_b32_e32 v28, v28, v26
	v_lshl_add_u64 v[36:37], v[24:25], 0, s[6:7]
	v_lshl_add_u64 v[36:37], v[36:37], 0, v[28:29]
	s_lshl_b32 s5, s96, 5
	s_lshr_b32 s6, s4, 4
	s_add_i32 s5, s5, s6
	v_add_u32_e32 v24, s5, v23
	v_mov_b32_e32 v25, 0
	v_lshlrev_b64 v[24:25], 12, v[24:25]
	v_lshl_add_u64 v[24:25], s[78:79], 0, v[24:25]
	s_and_b32 s5, s4, 64
	s_add_i32 vcc_lo, s5, 0
	v_xor_b32_e32 v28, vcc_lo, v27
	v_or_b32_e32 v28, v28, v26
	s_mov_b32 s6, 0x70400000
	v_lshl_add_u64 v[38:39], v[24:25], 0, s[6:7]
	v_lshl_add_u64 v[38:39], v[38:39], 0, v[28:29]
	s_add_i32 vcc_lo, s5, 32
	v_xor_b32_e32 v28, vcc_lo, v27
	v_or_b32_e32 v28, v28, v26
	s_mov_b32 s6, 0x70402000
	v_lshl_add_u64 v[40:41], v[24:25], 0, s[6:7]
	v_lshl_add_u64 v[40:41], v[40:41], 0, v[28:29]
	v_and_b32_e32 v42, 15, v0
	v_lshlrev_b32_e32 v43, 9, v42
	v_and_b32_e32 v44, 7, v42
	v_lshl_or_b32 v43, v44, 4, v43
	v_lshrrev_b32_e32 v44, 4, v22
	v_lshl_or_b32 v43, v44, 7, v43
	s_lshr_b32 s5, s4, 7
	s_lshl_b32 s5, s5, 13
	s_add_i32 s5, s5, 0x8000
	v_add_u32_e32 v42, s5, v43
	s_and_b32 s5, s4, 64
	s_lshl_b32 s5, s5, 7
	s_add_i32 s5, s5, 0x10000
	v_add_u32_e32 v43, s5, v43
	s_lshl_b32 s5, s4, 6
	s_lshl_b32 s6, s4, 5
	s_mov_b64 vcc, 0x80
	s_add_i32 m0, s5, 0x8000
	s_nop 0
	global_load_lds_dwordx4 v[30:31], off
	s_add_i32 m0, s5, 0x8400
	s_nop 0
	global_load_lds_dwordx4 v[32:33], off
	s_add_i32 m0, s5, 0x8800
	s_nop 0
	global_load_lds_dwordx4 v[34:35], off
	s_add_i32 m0, s5, 0x8c00
	s_nop 0
	global_load_lds_dwordx4 v[36:37], off
	s_add_i32 m0, s6, 0x10000
	s_nop 0
	global_load_lds_dwordx4 v[38:39], off
	s_add_i32 m0, s6, 0x10400
	s_nop 0
	global_load_lds_dwordx4 v[40:41], off
	v_lshl_add_u64 v[30:31], v[30:31], 0, vcc
	v_lshl_add_u64 v[32:33], v[32:33], 0, vcc
	v_lshl_add_u64 v[34:35], v[34:35], 0, vcc
	v_lshl_add_u64 v[36:37], v[36:37], 0, vcc
	v_lshl_add_u64 v[38:39], v[38:39], 0, vcc
	v_lshl_add_u64 v[40:41], v[40:41], 0, vcc
	s_add_i32 m0, s5, 0x14000
	s_nop 0
	global_load_lds_dwordx4 v[30:31], off
	s_add_i32 m0, s5, 0x14400
	s_nop 0
	global_load_lds_dwordx4 v[32:33], off
	s_add_i32 m0, s5, 0x14800
	s_nop 0
	global_load_lds_dwordx4 v[34:35], off
	s_add_i32 m0, s5, 0x14c00
	s_nop 0
	global_load_lds_dwordx4 v[36:37], off
	s_add_i32 m0, s6, 0x1c000
	s_nop 0
	global_load_lds_dwordx4 v[38:39], off
	s_add_i32 m0, s6, 0x1c400
	s_nop 0
	global_load_lds_dwordx4 v[40:41], off
	v_lshl_add_u64 v[30:31], v[30:31], 0, vcc
	v_lshl_add_u64 v[32:33], v[32:33], 0, vcc
	v_lshl_add_u64 v[34:35], v[34:35], 0, vcc
	v_lshl_add_u64 v[36:37], v[36:37], 0, vcc
	v_lshl_add_u64 v[38:39], v[38:39], 0, vcc
	v_lshl_add_u64 v[40:41], v[40:41], 0, vcc
	s_waitcnt vmcnt(6)
	s_barrier
	ds_read_b128 v[46:49], v42
	ds_read_b128 v[78:81], v43
	v_xor_b32_e32 v44, 16, v42
	v_xor_b32_e32 v45, 16, v43
	ds_read_b128 v[50:53], v44
	ds_read_b128 v[82:85], v45
	v_xor_b32_e32 v44, 32, v42
	v_xor_b32_e32 v45, 32, v43
	ds_read_b128 v[54:57], v44
	ds_read_b128 v[86:89], v45
	v_xor_b32_e32 v44, 48, v42
	v_xor_b32_e32 v45, 48, v43
	ds_read_b128 v[58:61], v44
	ds_read_b128 v[90:93], v45
	v_xor_b32_e32 v44, 64, v42
	v_xor_b32_e32 v45, 64, v43
	ds_read_b128 v[62:65], v44
	ds_read_b128 v[94:97], v45
	v_xor_b32_e32 v44, 0x50, v42
	v_xor_b32_e32 v45, 0x50, v43
	ds_read_b128 v[66:69], v44
	ds_read_b128 v[98:101], v45
	v_xor_b32_e32 v44, 0x60, v42
	v_xor_b32_e32 v45, 0x60, v43
	ds_read_b128 v[70:73], v44
	ds_read_b128 v[102:105], v45
	v_xor_b32_e32 v44, 0x70, v42
	v_xor_b32_e32 v45, 0x70, v43
	ds_read_b128 v[74:77], v44
	ds_read_b128 v[106:109], v45
	s_waitcnt lgkmcnt(14)
	v_mfma_f32_16x16x4_f32 v[18:21], v78, v46, v[18:21]
	v_mfma_f32_16x16x4_f32 v[18:21], v79, v47, v[18:21]
	v_mfma_f32_16x16x4_f32 v[18:21], v80, v48, v[18:21]
	v_mfma_f32_16x16x4_f32 v[18:21], v81, v49, v[18:21]
	s_waitcnt lgkmcnt(12)
	v_mfma_f32_16x16x4_f32 v[18:21], v82, v50, v[18:21]
	v_mfma_f32_16x16x4_f32 v[18:21], v83, v51, v[18:21]
	v_mfma_f32_16x16x4_f32 v[18:21], v84, v52, v[18:21]
	v_mfma_f32_16x16x4_f32 v[18:21], v85, v53, v[18:21]
	s_waitcnt lgkmcnt(10)
	v_mfma_f32_16x16x4_f32 v[18:21], v86, v54, v[18:21]
	v_mfma_f32_16x16x4_f32 v[18:21], v87, v55, v[18:21]
	v_mfma_f32_16x16x4_f32 v[18:21], v88, v56, v[18:21]
	v_mfma_f32_16x16x4_f32 v[18:21], v89, v57, v[18:21]
	s_waitcnt lgkmcnt(8)
	v_mfma_f32_16x16x4_f32 v[18:21], v90, v58, v[18:21]
	v_mfma_f32_16x16x4_f32 v[18:21], v91, v59, v[18:21]
	v_mfma_f32_16x16x4_f32 v[18:21], v92, v60, v[18:21]
	v_mfma_f32_16x16x4_f32 v[18:21], v93, v61, v[18:21]
	s_waitcnt vmcnt(0)
	s_waitcnt lgkmcnt(0)
	s_barrier
; __device__ __forceinline__ void phase_row1(const Frame& F, int l) {
;     ...
;             const int fr = lane & 15, fq = lane >> 4, tile = w >> 1, nt = w & 1;
;             const float* wp = (const float*)(F.ws + WS_RWT) + ((size_t)l * NE + 16 * nt + fr) * D + 256 * fq;
;             const float* hp = H32 + (size_t)(chunk * 64 + 16 * tile + fr) * D + 256 * fq;
;             f32x4 c = {0.f, 0.f, 0.f, 0.f};
; #pragma unroll 16
;             for (int s4 = 0; s4 < 256; s4 += 4) { const f32x4 a = *(const f32x4*)(wp + s4), bq = *(const f32x4*)(hp + s4);
;                 c = __builtin_amdgcn_mfma_f32_16x16x4f32(a.x, bq.x, c, 0, 0, 0); c = __builtin_amdgcn_mfma_f32_16x16x4f32(a.y, bq.y, c, 0, 0, 0);
;                 c = __builtin_amdgcn_mfma_f32_16x16x4f32(a.z, bq.z, c, 0, 0, 0); c = __builtin_amdgcn_mfma_f32_16x16x4f32(a.w, bq.w, c, 0, 0, 0); }
	s_add_i32 m0, s5, 0x8000
	s_nop 0
	global_load_lds_dwordx4 v[30:31], off
	s_add_i32 m0, s5, 0x8400
	s_nop 0
	global_load_lds_dwordx4 v[32:33], off
	s_add_i32 m0, s5, 0x8800
	s_nop 0
	global_load_lds_dwordx4 v[34:35], off
	s_add_i32 m0, s5, 0x8c00
	s_nop 0
	global_load_lds_dwordx4 v[36:37], off
	s_add_i32 m0, s6, 0x10000
	s_nop 0
	global_load_lds_dwordx4 v[38:39], off
	s_add_i32 m0, s6, 0x10400
	s_nop 0
	global_load_lds_dwordx4 v[40:41], off
	v_lshl_add_u64 v[30:31], v[30:31], 0, vcc
	v_lshl_add_u64 v[32:33], v[32:33], 0, vcc
	v_lshl_add_u64 v[34:35], v[34:35], 0, vcc
	v_lshl_add_u64 v[36:37], v[36:37], 0, vcc
	v_lshl_add_u64 v[38:39], v[38:39], 0, vcc
	v_lshl_add_u64 v[40:41], v[40:41], 0, vcc
	ds_read_b128 v[46:49], v42 offset:49152
	ds_read_b128 v[78:81], v43 offset:49152
	v_xor_b32_e32 v44, 16, v42
	v_xor_b32_e32 v45, 16, v43
	ds_read_b128 v[50:53], v44 offset:49152
	ds_read_b128 v[82:85], v45 offset:49152
	v_xor_b32_e32 v44, 32, v42
	v_xor_b32_e32 v45, 32, v43
	ds_read_b128 v[54:57], v44 offset:49152
	ds_read_b128 v[86:89], v45 offset:49152
	v_xor_b32_e32 v44, 48, v42
	v_xor_b32_e32 v45, 48, v43
	ds_read_b128 v[58:61], v44 offset:49152
	ds_read_b128 v[90:93], v45 offset:49152
	s_waitcnt lgkmcnt(14)
	v_mfma_f32_16x16x4_f32 v[18:21], v94, v62, v[18:21]
	v_mfma_f32_16x16x4_f32 v[18:21], v95, v63, v[18:21]
	v_mfma_f32_16x16x4_f32 v[18:21], v96, v64, v[18:21]
	v_mfma_f32_16x16x4_f32 v[18:21], v97, v65, v[18:21]
	s_waitcnt lgkmcnt(12)
	v_mfma_f32_16x16x4_f32 v[18:21], v98, v66, v[18:21]
	v_mfma_f32_16x16x4_f32 v[18:21], v99, v67, v[18:21]
	v_mfma_f32_16x16x4_f32 v[18:21], v100, v68, v[18:21]
	v_mfma_f32_16x16x4_f32 v[18:21], v101, v69, v[18:21]
	s_waitcnt lgkmcnt(10)
	v_mfma_f32_16x16x4_f32 v[18:21], v102, v70, v[18:21]
	v_mfma_f32_16x16x4_f32 v[18:21], v103, v71, v[18:21]
	v_mfma_f32_16x16x4_f32 v[18:21], v104, v72, v[18:21]
	v_mfma_f32_16x16x4_f32 v[18:21], v105, v73, v[18:21]
	s_waitcnt lgkmcnt(8)
	v_mfma_f32_16x16x4_f32 v[18:21], v106, v74, v[18:21]
	v_mfma_f32_16x16x4_f32 v[18:21], v107, v75, v[18:21]
	v_mfma_f32_16x16x4_f32 v[18:21], v108, v76, v[18:21]
	v_mfma_f32_16x16x4_f32 v[18:21], v109, v77, v[18:21]
	v_xor_b32_e32 v44, 64, v42
	v_xor_b32_e32 v45, 64, v43
	ds_read_b128 v[62:65], v44 offset:49152
	ds_read_b128 v[94:97], v45 offset:49152
	v_xor_b32_e32 v44, 0x50, v42
	v_xor_b32_e32 v45, 0x50, v43
	ds_read_b128 v[66:69], v44 offset:49152
	ds_read_b128 v[98:101], v45 offset:49152
	v_xor_b32_e32 v44, 0x60, v42
	v_xor_b32_e32 v45, 0x60, v43
	ds_read_b128 v[70:73], v44 offset:49152
	ds_read_b128 v[102:105], v45 offset:49152
	v_xor_b32_e32 v44, 0x70, v42
	v_xor_b32_e32 v45, 0x70, v43
	ds_read_b128 v[74:77], v44 offset:49152
	ds_read_b128 v[106:109], v45 offset:49152
	s_waitcnt lgkmcnt(14)
	v_mfma_f32_16x16x4_f32 v[18:21], v78, v46, v[18:21]
	v_mfma_f32_16x16x4_f32 v[18:21], v79, v47, v[18:21]
	v_mfma_f32_16x16x4_f32 v[18:21], v80, v48, v[18:21]
	v_mfma_f32_16x16x4_f32 v[18:21], v81, v49, v[18:21]
	s_waitcnt lgkmcnt(12)
	v_mfma_f32_16x16x4_f32 v[18:21], v82, v50, v[18:21]
	v_mfma_f32_16x16x4_f32 v[18:21], v83, v51, v[18:21]
	v_mfma_f32_16x16x4_f32 v[18:21], v84, v52, v[18:21]
	v_mfma_f32_16x16x4_f32 v[18:21], v85, v53, v[18:21]
	s_waitcnt lgkmcnt(10)
	v_mfma_f32_16x16x4_f32 v[18:21], v86, v54, v[18:21]
	v_mfma_f32_16x16x4_f32 v[18:21], v87, v55, v[18:21]
	v_mfma_f32_16x16x4_f32 v[18:21], v88, v56, v[18:21]
	v_mfma_f32_16x16x4_f32 v[18:21], v89, v57, v[18:21]
	s_waitcnt lgkmcnt(8)
	v_mfma_f32_16x16x4_f32 v[18:21], v90, v58, v[18:21]
	v_mfma_f32_16x16x4_f32 v[18:21], v91, v59, v[18:21]
	v_mfma_f32_16x16x4_f32 v[18:21], v92, v60, v[18:21]
	v_mfma_f32_16x16x4_f32 v[18:21], v93, v61, v[18:21]
	s_waitcnt vmcnt(0)
	s_waitcnt lgkmcnt(0)
	s_barrier
	s_add_i32 m0, s5, 0x14000
	s_nop 0
	global_load_lds_dwordx4 v[30:31], off
	s_add_i32 m0, s5, 0x14400
	s_nop 0
	global_load_lds_dwordx4 v[32:33], off
	s_add_i32 m0, s5, 0x14800
	s_nop 0
	global_load_lds_dwordx4 v[34:35], off
	s_add_i32 m0, s5, 0x14c00
	s_nop 0
	global_load_lds_dwordx4 v[36:37], off
	s_add_i32 m0, s6, 0x1c000
	s_nop 0
	global_load_lds_dwordx4 v[38:39], off
	s_add_i32 m0, s6, 0x1c400
	s_nop 0
	global_load_lds_dwordx4 v[40:41], off
	v_lshl_add_u64 v[30:31], v[30:31], 0, vcc
	v_lshl_add_u64 v[32:33], v[32:33], 0, vcc
	v_lshl_add_u64 v[34:35], v[34:35], 0, vcc
	v_lshl_add_u64 v[36:37], v[36:37], 0, vcc
	v_lshl_add_u64 v[38:39], v[38:39], 0, vcc
	v_lshl_add_u64 v[40:41], v[40:41], 0, vcc
	ds_read_b128 v[46:49], v42
	ds_read_b128 v[78:81], v43
	v_xor_b32_e32 v44, 16, v42
	v_xor_b32_e32 v45, 16, v43
	ds_read_b128 v[50:53], v44
	ds_read_b128 v[82:85], v45
	v_xor_b32_e32 v44, 32, v42
	v_xor_b32_e32 v45, 32, v43
	ds_read_b128 v[54:57], v44
	ds_read_b128 v[86:89], v45
	v_xor_b32_e32 v44, 48, v42
	v_xor_b32_e32 v45, 48, v43
	ds_read_b128 v[58:61], v44
	ds_read_b128 v[90:93], v45
	s_waitcnt lgkmcnt(14)
	v_mfma_f32_16x16x4_f32 v[18:21], v94, v62, v[18:21]
	v_mfma_f32_16x16x4_f32 v[18:21], v95, v63, v[18:21]
	v_mfma_f32_16x16x4_f32 v[18:21], v96, v64, v[18:21]
	v_mfma_f32_16x16x4_f32 v[18:21], v97, v65, v[18:21]
	s_waitcnt lgkmcnt(12)
	v_mfma_f32_16x16x4_f32 v[18:21], v98, v66, v[18:21]
	v_mfma_f32_16x16x4_f32 v[18:21], v99, v67, v[18:21]
	v_mfma_f32_16x16x4_f32 v[18:21], v100, v68, v[18:21]
	v_mfma_f32_16x16x4_f32 v[18:21], v101, v69, v[18:21]
	s_waitcnt lgkmcnt(10)
	v_mfma_f32_16x16x4_f32 v[18:21], v102, v70, v[18:21]
	v_mfma_f32_16x16x4_f32 v[18:21], v103, v71, v[18:21]
	v_mfma_f32_16x16x4_f32 v[18:21], v104, v72, v[18:21]
	v_mfma_f32_16x16x4_f32 v[18:21], v105, v73, v[18:21]
	s_waitcnt lgkmcnt(8)
; __device__ __forceinline__ void phase_row1(const Frame& F, int l) {
;     ...
;             const int fr = lane & 15, fq = lane >> 4, tile = w >> 1, nt = w & 1;
;             const float* wp = (const float*)(F.ws + WS_RWT) + ((size_t)l * NE + 16 * nt + fr) * D + 256 * fq;
;             const float* hp = H32 + (size_t)(chunk * 64 + 16 * tile + fr) * D + 256 * fq;
;             f32x4 c = {0.f, 0.f, 0.f, 0.f};
; #pragma unroll 16
;             for (int s4 = 0; s4 < 256; s4 += 4) { const f32x4 a = *(const f32x4*)(wp + s4), bq = *(const f32x4*)(hp + s4);
;                 c = __builtin_amdgcn_mfma_f32_16x16x4f32(a.x, bq.x, c, 0, 0, 0); c = __builtin_amdgcn_mfma_f32_16x16x4f32(a.y, bq.y, c, 0, 0, 0);
;                 c = __builtin_amdgcn_mfma_f32_16x16x4f32(a.z, bq.z, c, 0, 0, 0); c = __builtin_amdgcn_mfma_f32_16x16x4f32(a.w, bq.w, c, 0, 0, 0); }
	v_mfma_f32_16x16x4_f32 v[18:21], v106, v74, v[18:21]
	v_mfma_f32_16x16x4_f32 v[18:21], v107, v75, v[18:21]
	v_mfma_f32_16x16x4_f32 v[18:21], v108, v76, v[18:21]
	v_mfma_f32_16x16x4_f32 v[18:21], v109, v77, v[18:21]
	v_xor_b32_e32 v44, 64, v42
	v_xor_b32_e32 v45, 64, v43
	ds_read_b128 v[62:65], v44
	ds_read_b128 v[94:97], v45
	v_xor_b32_e32 v44, 0x50, v42
	v_xor_b32_e32 v45, 0x50, v43
	ds_read_b128 v[66:69], v44
	ds_read_b128 v[98:101], v45
	v_xor_b32_e32 v44, 0x60, v42
	v_xor_b32_e32 v45, 0x60, v43
	ds_read_b128 v[70:73], v44
	ds_read_b128 v[102:105], v45
	v_xor_b32_e32 v44, 0x70, v42
	v_xor_b32_e32 v45, 0x70, v43
	ds_read_b128 v[74:77], v44
	ds_read_b128 v[106:109], v45
	s_waitcnt lgkmcnt(14)
	v_mfma_f32_16x16x4_f32 v[18:21], v78, v46, v[18:21]
	v_mfma_f32_16x16x4_f32 v[18:21], v79, v47, v[18:21]
	v_mfma_f32_16x16x4_f32 v[18:21], v80, v48, v[18:21]
	v_mfma_f32_16x16x4_f32 v[18:21], v81, v49, v[18:21]
	s_waitcnt lgkmcnt(12)
	v_mfma_f32_16x16x4_f32 v[18:21], v82, v50, v[18:21]
	v_mfma_f32_16x16x4_f32 v[18:21], v83, v51, v[18:21]
	v_mfma_f32_16x16x4_f32 v[18:21], v84, v52, v[18:21]
	v_mfma_f32_16x16x4_f32 v[18:21], v85, v53, v[18:21]
	s_waitcnt lgkmcnt(10)
	v_mfma_f32_16x16x4_f32 v[18:21], v86, v54, v[18:21]
	v_mfma_f32_16x16x4_f32 v[18:21], v87, v55, v[18:21]
	v_mfma_f32_16x16x4_f32 v[18:21], v88, v56, v[18:21]
	v_mfma_f32_16x16x4_f32 v[18:21], v89, v57, v[18:21]
	s_waitcnt lgkmcnt(8)
	v_mfma_f32_16x16x4_f32 v[18:21], v90, v58, v[18:21]
	v_mfma_f32_16x16x4_f32 v[18:21], v91, v59, v[18:21]
	v_mfma_f32_16x16x4_f32 v[18:21], v92, v60, v[18:21]
	v_mfma_f32_16x16x4_f32 v[18:21], v93, v61, v[18:21]
	s_waitcnt vmcnt(0)
	s_waitcnt lgkmcnt(0)
	s_barrier
	s_add_i32 m0, s5, 0x8000
	s_nop 0
	global_load_lds_dwordx4 v[30:31], off
	s_add_i32 m0, s5, 0x8400
	s_nop 0
	global_load_lds_dwordx4 v[32:33], off
	s_add_i32 m0, s5, 0x8800
	s_nop 0
	global_load_lds_dwordx4 v[34:35], off
	s_add_i32 m0, s5, 0x8c00
	s_nop 0
	global_load_lds_dwordx4 v[36:37], off
	s_add_i32 m0, s6, 0x10000
	s_nop 0
	global_load_lds_dwordx4 v[38:39], off
	s_add_i32 m0, s6, 0x10400
	s_nop 0
	global_load_lds_dwordx4 v[40:41], off
	v_lshl_add_u64 v[30:31], v[30:31], 0, vcc
	v_lshl_add_u64 v[32:33], v[32:33], 0, vcc
	v_lshl_add_u64 v[34:35], v[34:35], 0, vcc
	v_lshl_add_u64 v[36:37], v[36:37], 0, vcc
	v_lshl_add_u64 v[38:39], v[38:39], 0, vcc
	v_lshl_add_u64 v[40:41], v[40:41], 0, vcc
	ds_read_b128 v[46:49], v42 offset:49152
	ds_read_b128 v[78:81], v43 offset:49152
	v_xor_b32_e32 v44, 16, v42
	v_xor_b32_e32 v45, 16, v43
	ds_read_b128 v[50:53], v44 offset:49152
	ds_read_b128 v[82:85], v45 offset:49152
	v_xor_b32_e32 v44, 32, v42
	v_xor_b32_e32 v45, 32, v43
	ds_read_b128 v[54:57], v44 offset:49152
	ds_read_b128 v[86:89], v45 offset:49152
	v_xor_b32_e32 v44, 48, v42
	v_xor_b32_e32 v45, 48, v43
	ds_read_b128 v[58:61], v44 offset:49152
	ds_read_b128 v[90:93], v45 offset:49152
	s_waitcnt lgkmcnt(14)
	v_mfma_f32_16x16x4_f32 v[18:21], v94, v62, v[18:21]
	v_mfma_f32_16x16x4_f32 v[18:21], v95, v63, v[18:21]
	v_mfma_f32_16x16x4_f32 v[18:21], v96, v64, v[18:21]
	v_mfma_f32_16x16x4_f32 v[18:21], v97, v65, v[18:21]
	s_waitcnt lgkmcnt(12)
	v_mfma_f32_16x16x4_f32 v[18:21], v98, v66, v[18:21]
	v_mfma_f32_16x16x4_f32 v[18:21], v99, v67, v[18:21]
	v_mfma_f32_16x16x4_f32 v[18:21], v100, v68, v[18:21]
	v_mfma_f32_16x16x4_f32 v[18:21], v101, v69, v[18:21]
	s_waitcnt lgkmcnt(10)
	v_mfma_f32_16x16x4_f32 v[18:21], v102, v70, v[18:21]
	v_mfma_f32_16x16x4_f32 v[18:21], v103, v71, v[18:21]
	v_mfma_f32_16x16x4_f32 v[18:21], v104, v72, v[18:21]
	v_mfma_f32_16x16x4_f32 v[18:21], v105, v73, v[18:21]
	s_waitcnt lgkmcnt(8)
	v_mfma_f32_16x16x4_f32 v[18:21], v106, v74, v[18:21]
	v_mfma_f32_16x16x4_f32 v[18:21], v107, v75, v[18:21]
	v_mfma_f32_16x16x4_f32 v[18:21], v108, v76, v[18:21]
	v_mfma_f32_16x16x4_f32 v[18:21], v109, v77, v[18:21]
	v_xor_b32_e32 v44, 64, v42
	v_xor_b32_e32 v45, 64, v43
	ds_read_b128 v[62:65], v44 offset:49152
	ds_read_b128 v[94:97], v45 offset:49152
	v_xor_b32_e32 v44, 0x50, v42
	v_xor_b32_e32 v45, 0x50, v43
	ds_read_b128 v[66:69], v44 offset:49152
	ds_read_b128 v[98:101], v45 offset:49152
	v_xor_b32_e32 v44, 0x60, v42
	v_xor_b32_e32 v45, 0x60, v43
	ds_read_b128 v[70:73], v44 offset:49152
	ds_read_b128 v[102:105], v45 offset:49152
	v_xor_b32_e32 v44, 0x70, v42
	v_xor_b32_e32 v45, 0x70, v43
	ds_read_b128 v[74:77], v44 offset:49152
	ds_read_b128 v[106:109], v45 offset:49152
	s_waitcnt lgkmcnt(14)
	v_mfma_f32_16x16x4_f32 v[18:21], v78, v46, v[18:21]
	v_mfma_f32_16x16x4_f32 v[18:21], v79, v47, v[18:21]
	v_mfma_f32_16x16x4_f32 v[18:21], v80, v48, v[18:21]
	v_mfma_f32_16x16x4_f32 v[18:21], v81, v49, v[18:21]
	s_waitcnt lgkmcnt(12)
	v_mfma_f32_16x16x4_f32 v[18:21], v82, v50, v[18:21]
	v_mfma_f32_16x16x4_f32 v[18:21], v83, v51, v[18:21]
	v_mfma_f32_16x16x4_f32 v[18:21], v84, v52, v[18:21]
	v_mfma_f32_16x16x4_f32 v[18:21], v85, v53, v[18:21]
	s_waitcnt lgkmcnt(10)
	v_mfma_f32_16x16x4_f32 v[18:21], v86, v54, v[18:21]
	v_mfma_f32_16x16x4_f32 v[18:21], v87, v55, v[18:21]
	v_mfma_f32_16x16x4_f32 v[18:21], v88, v56, v[18:21]
	v_mfma_f32_16x16x4_f32 v[18:21], v89, v57, v[18:21]
	s_waitcnt lgkmcnt(8)
	v_mfma_f32_16x16x4_f32 v[18:21], v90, v58, v[18:21]
	v_mfma_f32_16x16x4_f32 v[18:21], v91, v59, v[18:21]
	v_mfma_f32_16x16x4_f32 v[18:21], v92, v60, v[18:21]
	v_mfma_f32_16x16x4_f32 v[18:21], v93, v61, v[18:21]
	s_waitcnt vmcnt(0)
	s_waitcnt lgkmcnt(0)
	s_barrier
; __device__ __forceinline__ void phase_row1(const Frame& F, int l) {
;     ...
;             const int fr = lane & 15, fq = lane >> 4, tile = w >> 1, nt = w & 1;
;             const float* wp = (const float*)(F.ws + WS_RWT) + ((size_t)l * NE + 16 * nt + fr) * D + 256 * fq;
;             const float* hp = H32 + (size_t)(chunk * 64 + 16 * tile + fr) * D + 256 * fq;
;             f32x4 c = {0.f, 0.f, 0.f, 0.f};
; #pragma unroll 16
;             for (int s4 = 0; s4 < 256; s4 += 4) { const f32x4 a = *(const f32x4*)(wp + s4), bq = *(const f32x4*)(hp + s4);
;                 c = __builtin_amdgcn_mfma_f32_16x16x4f32(a.x, bq.x, c, 0, 0, 0); c = __builtin_amdgcn_mfma_f32_16x16x4f32(a.y, bq.y, c, 0, 0, 0);
;                 c = __builtin_amdgcn_mfma_f32_16x16x4f32(a.z, bq.z, c, 0, 0, 0); c = __builtin_amdgcn_mfma_f32_16x16x4f32(a.w, bq.w, c, 0, 0, 0); }
	s_add_i32 m0, s5, 0x14000
	s_nop 0
	global_load_lds_dwordx4 v[30:31], off
	s_add_i32 m0, s5, 0x14400
	s_nop 0
	global_load_lds_dwordx4 v[32:33], off
	s_add_i32 m0, s5, 0x14800
	s_nop 0
	global_load_lds_dwordx4 v[34:35], off
	s_add_i32 m0, s5, 0x14c00
	s_nop 0
	global_load_lds_dwordx4 v[36:37], off
	s_add_i32 m0, s6, 0x1c000
	s_nop 0
	global_load_lds_dwordx4 v[38:39], off
	s_add_i32 m0, s6, 0x1c400
	s_nop 0
	global_load_lds_dwordx4 v[40:41], off
	v_lshl_add_u64 v[30:31], v[30:31], 0, vcc
	v_lshl_add_u64 v[32:33], v[32:33], 0, vcc
	v_lshl_add_u64 v[34:35], v[34:35], 0, vcc
	v_lshl_add_u64 v[36:37], v[36:37], 0, vcc
	v_lshl_add_u64 v[38:39], v[38:39], 0, vcc
	v_lshl_add_u64 v[40:41], v[40:41], 0, vcc
	ds_read_b128 v[46:49], v42
	ds_read_b128 v[78:81], v43
	v_xor_b32_e32 v44, 16, v42
	v_xor_b32_e32 v45, 16, v43
	ds_read_b128 v[50:53], v44
	ds_read_b128 v[82:85], v45
	v_xor_b32_e32 v44, 32, v42
	v_xor_b32_e32 v45, 32, v43
	ds_read_b128 v[54:57], v44
	ds_read_b128 v[86:89], v45
	v_xor_b32_e32 v44, 48, v42
	v_xor_b32_e32 v45, 48, v43
	ds_read_b128 v[58:61], v44
	ds_read_b128 v[90:93], v45
	s_waitcnt lgkmcnt(14)
	v_mfma_f32_16x16x4_f32 v[18:21], v94, v62, v[18:21]
	v_mfma_f32_16x16x4_f32 v[18:21], v95, v63, v[18:21]
	v_mfma_f32_16x16x4_f32 v[18:21], v96, v64, v[18:21]
	v_mfma_f32_16x16x4_f32 v[18:21], v97, v65, v[18:21]
	s_waitcnt lgkmcnt(12)
	v_mfma_f32_16x16x4_f32 v[18:21], v98, v66, v[18:21]
	v_mfma_f32_16x16x4_f32 v[18:21], v99, v67, v[18:21]
	v_mfma_f32_16x16x4_f32 v[18:21], v100, v68, v[18:21]
	v_mfma_f32_16x16x4_f32 v[18:21], v101, v69, v[18:21]
	s_waitcnt lgkmcnt(10)
	v_mfma_f32_16x16x4_f32 v[18:21], v102, v70, v[18:21]
	v_mfma_f32_16x16x4_f32 v[18:21], v103, v71, v[18:21]
	v_mfma_f32_16x16x4_f32 v[18:21], v104, v72, v[18:21]
	v_mfma_f32_16x16x4_f32 v[18:21], v105, v73, v[18:21]
	s_waitcnt lgkmcnt(8)
	v_mfma_f32_16x16x4_f32 v[18:21], v106, v74, v[18:21]
	v_mfma_f32_16x16x4_f32 v[18:21], v107, v75, v[18:21]
	v_mfma_f32_16x16x4_f32 v[18:21], v108, v76, v[18:21]
	v_mfma_f32_16x16x4_f32 v[18:21], v109, v77, v[18:21]
	v_xor_b32_e32 v44, 64, v42
	v_xor_b32_e32 v45, 64, v43
	ds_read_b128 v[62:65], v44
	ds_read_b128 v[94:97], v45
	v_xor_b32_e32 v44, 0x50, v42
	v_xor_b32_e32 v45, 0x50, v43
	ds_read_b128 v[66:69], v44
	ds_read_b128 v[98:101], v45
	v_xor_b32_e32 v44, 0x60, v42
	v_xor_b32_e32 v45, 0x60, v43
	ds_read_b128 v[70:73], v44
	ds_read_b128 v[102:105], v45
	v_xor_b32_e32 v44, 0x70, v42
	v_xor_b32_e32 v45, 0x70, v43
	ds_read_b128 v[74:77], v44
	ds_read_b128 v[106:109], v45
	s_waitcnt lgkmcnt(14)
	v_mfma_f32_16x16x4_f32 v[18:21], v78, v46, v[18:21]
	v_mfma_f32_16x16x4_f32 v[18:21], v79, v47, v[18:21]
	v_mfma_f32_16x16x4_f32 v[18:21], v80, v48, v[18:21]
	v_mfma_f32_16x16x4_f32 v[18:21], v81, v49, v[18:21]
	s_waitcnt lgkmcnt(12)
	v_mfma_f32_16x16x4_f32 v[18:21], v82, v50, v[18:21]
	v_mfma_f32_16x16x4_f32 v[18:21], v83, v51, v[18:21]
	v_mfma_f32_16x16x4_f32 v[18:21], v84, v52, v[18:21]
	v_mfma_f32_16x16x4_f32 v[18:21], v85, v53, v[18:21]
	s_waitcnt lgkmcnt(10)
	v_mfma_f32_16x16x4_f32 v[18:21], v86, v54, v[18:21]
	v_mfma_f32_16x16x4_f32 v[18:21], v87, v55, v[18:21]
	v_mfma_f32_16x16x4_f32 v[18:21], v88, v56, v[18:21]
	v_mfma_f32_16x16x4_f32 v[18:21], v89, v57, v[18:21]
	s_waitcnt lgkmcnt(8)
	v_mfma_f32_16x16x4_f32 v[18:21], v90, v58, v[18:21]
	v_mfma_f32_16x16x4_f32 v[18:21], v91, v59, v[18:21]
	v_mfma_f32_16x16x4_f32 v[18:21], v92, v60, v[18:21]
	v_mfma_f32_16x16x4_f32 v[18:21], v93, v61, v[18:21]
	s_waitcnt vmcnt(0)
	s_waitcnt lgkmcnt(0)
	s_barrier
	s_add_i32 m0, s5, 0x8000
	s_nop 0
	global_load_lds_dwordx4 v[30:31], off
	s_add_i32 m0, s5, 0x8400
	s_nop 0
	global_load_lds_dwordx4 v[32:33], off
	s_add_i32 m0, s5, 0x8800
	s_nop 0
	global_load_lds_dwordx4 v[34:35], off
	s_add_i32 m0, s5, 0x8c00
	s_nop 0
	global_load_lds_dwordx4 v[36:37], off
	s_add_i32 m0, s6, 0x10000
	s_nop 0
	global_load_lds_dwordx4 v[38:39], off
	s_add_i32 m0, s6, 0x10400
	s_nop 0
	global_load_lds_dwordx4 v[40:41], off
	v_lshl_add_u64 v[30:31], v[30:31], 0, vcc
	v_lshl_add_u64 v[32:33], v[32:33], 0, vcc
	v_lshl_add_u64 v[34:35], v[34:35], 0, vcc
	v_lshl_add_u64 v[36:37], v[36:37], 0, vcc
	v_lshl_add_u64 v[38:39], v[38:39], 0, vcc
	v_lshl_add_u64 v[40:41], v[40:41], 0, vcc
	ds_read_b128 v[46:49], v42 offset:49152
	ds_read_b128 v[78:81], v43 offset:49152
	v_xor_b32_e32 v44, 16, v42
	v_xor_b32_e32 v45, 16, v43
	ds_read_b128 v[50:53], v44 offset:49152
	ds_read_b128 v[82:85], v45 offset:49152
	v_xor_b32_e32 v44, 32, v42
	v_xor_b32_e32 v45, 32, v43
	ds_read_b128 v[54:57], v44 offset:49152
	ds_read_b128 v[86:89], v45 offset:49152
	v_xor_b32_e32 v44, 48, v42
	v_xor_b32_e32 v45, 48, v43
	ds_read_b128 v[58:61], v44 offset:49152
	ds_read_b128 v[90:93], v45 offset:49152
	s_waitcnt lgkmcnt(14)
	v_mfma_f32_16x16x4_f32 v[18:21], v94, v62, v[18:21]
	v_mfma_f32_16x16x4_f32 v[18:21], v95, v63, v[18:21]
	v_mfma_f32_16x16x4_f32 v[18:21], v96, v64, v[18:21]
	v_mfma_f32_16x16x4_f32 v[18:21], v97, v65, v[18:21]
	s_waitcnt lgkmcnt(12)
	v_mfma_f32_16x16x4_f32 v[18:21], v98, v66, v[18:21]
	v_mfma_f32_16x16x4_f32 v[18:21], v99, v67, v[18:21]
	v_mfma_f32_16x16x4_f32 v[18:21], v100, v68, v[18:21]
	v_mfma_f32_16x16x4_f32 v[18:21], v101, v69, v[18:21]
	s_waitcnt lgkmcnt(10)
	v_mfma_f32_16x16x4_f32 v[18:21], v102, v70, v[18:21]
	v_mfma_f32_16x16x4_f32 v[18:21], v103, v71, v[18:21]
	v_mfma_f32_16x16x4_f32 v[18:21], v104, v72, v[18:21]
	v_mfma_f32_16x16x4_f32 v[18:21], v105, v73, v[18:21]
	s_waitcnt lgkmcnt(8)
; __device__ __forceinline__ void phase_row1(const Frame& F, int l) {
;     ...
;             const int fr = lane & 15, fq = lane >> 4, tile = w >> 1, nt = w & 1;
;             const float* wp = (const float*)(F.ws + WS_RWT) + ((size_t)l * NE + 16 * nt + fr) * D + 256 * fq;
;             const float* hp = H32 + (size_t)(chunk * 64 + 16 * tile + fr) * D + 256 * fq;
;             f32x4 c = {0.f, 0.f, 0.f, 0.f};
; #pragma unroll 16
;             for (int s4 = 0; s4 < 256; s4 += 4) { const f32x4 a = *(const f32x4*)(wp + s4), bq = *(const f32x4*)(hp + s4);
;                 c = __builtin_amdgcn_mfma_f32_16x16x4f32(a.x, bq.x, c, 0, 0, 0); c = __builtin_amdgcn_mfma_f32_16x16x4f32(a.y, bq.y, c, 0, 0, 0);
;                 c = __builtin_amdgcn_mfma_f32_16x16x4f32(a.z, bq.z, c, 0, 0, 0); c = __builtin_amdgcn_mfma_f32_16x16x4f32(a.w, bq.w, c, 0, 0, 0); }
	v_mfma_f32_16x16x4_f32 v[18:21], v106, v74, v[18:21]
	v_mfma_f32_16x16x4_f32 v[18:21], v107, v75, v[18:21]
	v_mfma_f32_16x16x4_f32 v[18:21], v108, v76, v[18:21]
	v_mfma_f32_16x16x4_f32 v[18:21], v109, v77, v[18:21]
	v_xor_b32_e32 v44, 64, v42
	v_xor_b32_e32 v45, 64, v43
	ds_read_b128 v[62:65], v44 offset:49152
	ds_read_b128 v[94:97], v45 offset:49152
	v_xor_b32_e32 v44, 0x50, v42
	v_xor_b32_e32 v45, 0x50, v43
	ds_read_b128 v[66:69], v44 offset:49152
	ds_read_b128 v[98:101], v45 offset:49152
	v_xor_b32_e32 v44, 0x60, v42
	v_xor_b32_e32 v45, 0x60, v43
	ds_read_b128 v[70:73], v44 offset:49152
	ds_read_b128 v[102:105], v45 offset:49152
	v_xor_b32_e32 v44, 0x70, v42
	v_xor_b32_e32 v45, 0x70, v43
	ds_read_b128 v[74:77], v44 offset:49152
	ds_read_b128 v[106:109], v45 offset:49152
	s_waitcnt lgkmcnt(14)
	v_mfma_f32_16x16x4_f32 v[18:21], v78, v46, v[18:21]
	v_mfma_f32_16x16x4_f32 v[18:21], v79, v47, v[18:21]
	v_mfma_f32_16x16x4_f32 v[18:21], v80, v48, v[18:21]
	v_mfma_f32_16x16x4_f32 v[18:21], v81, v49, v[18:21]
	s_waitcnt lgkmcnt(12)
	v_mfma_f32_16x16x4_f32 v[18:21], v82, v50, v[18:21]
	v_mfma_f32_16x16x4_f32 v[18:21], v83, v51, v[18:21]
	v_mfma_f32_16x16x4_f32 v[18:21], v84, v52, v[18:21]
	v_mfma_f32_16x16x4_f32 v[18:21], v85, v53, v[18:21]
	s_waitcnt lgkmcnt(10)
	v_mfma_f32_16x16x4_f32 v[18:21], v86, v54, v[18:21]
	v_mfma_f32_16x16x4_f32 v[18:21], v87, v55, v[18:21]
	v_mfma_f32_16x16x4_f32 v[18:21], v88, v56, v[18:21]
	v_mfma_f32_16x16x4_f32 v[18:21], v89, v57, v[18:21]
	s_waitcnt lgkmcnt(8)
	v_mfma_f32_16x16x4_f32 v[18:21], v90, v58, v[18:21]
	v_mfma_f32_16x16x4_f32 v[18:21], v91, v59, v[18:21]
	v_mfma_f32_16x16x4_f32 v[18:21], v92, v60, v[18:21]
	v_mfma_f32_16x16x4_f32 v[18:21], v93, v61, v[18:21]
	s_waitcnt vmcnt(0)
	s_waitcnt lgkmcnt(0)
	s_barrier
	s_add_i32 m0, s5, 0x14000
	s_nop 0
	global_load_lds_dwordx4 v[30:31], off
	s_add_i32 m0, s5, 0x14400
	s_nop 0
	global_load_lds_dwordx4 v[32:33], off
	s_add_i32 m0, s5, 0x14800
	s_nop 0
	global_load_lds_dwordx4 v[34:35], off
	s_add_i32 m0, s5, 0x14c00
	s_nop 0
	global_load_lds_dwordx4 v[36:37], off
	s_add_i32 m0, s6, 0x1c000
	s_nop 0
	global_load_lds_dwordx4 v[38:39], off
	s_add_i32 m0, s6, 0x1c400
	s_nop 0
	global_load_lds_dwordx4 v[40:41], off
	v_lshl_add_u64 v[30:31], v[30:31], 0, vcc
	v_lshl_add_u64 v[32:33], v[32:33], 0, vcc
	v_lshl_add_u64 v[34:35], v[34:35], 0, vcc
	v_lshl_add_u64 v[36:37], v[36:37], 0, vcc
	v_lshl_add_u64 v[38:39], v[38:39], 0, vcc
	v_lshl_add_u64 v[40:41], v[40:41], 0, vcc
	ds_read_b128 v[46:49], v42
	ds_read_b128 v[78:81], v43
	v_xor_b32_e32 v44, 16, v42
	v_xor_b32_e32 v45, 16, v43
	ds_read_b128 v[50:53], v44
	ds_read_b128 v[82:85], v45
	v_xor_b32_e32 v44, 32, v42
	v_xor_b32_e32 v45, 32, v43
	ds_read_b128 v[54:57], v44
	ds_read_b128 v[86:89], v45
	v_xor_b32_e32 v44, 48, v42
	v_xor_b32_e32 v45, 48, v43
	ds_read_b128 v[58:61], v44
	ds_read_b128 v[90:93], v45
	s_waitcnt lgkmcnt(14)
	v_mfma_f32_16x16x4_f32 v[18:21], v94, v62, v[18:21]
	v_mfma_f32_16x16x4_f32 v[18:21], v95, v63, v[18:21]
	v_mfma_f32_16x16x4_f32 v[18:21], v96, v64, v[18:21]
	v_mfma_f32_16x16x4_f32 v[18:21], v97, v65, v[18:21]
	s_waitcnt lgkmcnt(12)
	v_mfma_f32_16x16x4_f32 v[18:21], v98, v66, v[18:21]
	v_mfma_f32_16x16x4_f32 v[18:21], v99, v67, v[18:21]
	v_mfma_f32_16x16x4_f32 v[18:21], v100, v68, v[18:21]
	v_mfma_f32_16x16x4_f32 v[18:21], v101, v69, v[18:21]
	s_waitcnt lgkmcnt(10)
	v_mfma_f32_16x16x4_f32 v[18:21], v102, v70, v[18:21]
	v_mfma_f32_16x16x4_f32 v[18:21], v103, v71, v[18:21]
	v_mfma_f32_16x16x4_f32 v[18:21], v104, v72, v[18:21]
	v_mfma_f32_16x16x4_f32 v[18:21], v105, v73, v[18:21]
	s_waitcnt lgkmcnt(8)
	v_mfma_f32_16x16x4_f32 v[18:21], v106, v74, v[18:21]
	v_mfma_f32_16x16x4_f32 v[18:21], v107, v75, v[18:21]
	v_mfma_f32_16x16x4_f32 v[18:21], v108, v76, v[18:21]
	v_mfma_f32_16x16x4_f32 v[18:21], v109, v77, v[18:21]
	v_xor_b32_e32 v44, 64, v42
	v_xor_b32_e32 v45, 64, v43
	ds_read_b128 v[62:65], v44
	ds_read_b128 v[94:97], v45
	v_xor_b32_e32 v44, 0x50, v42
	v_xor_b32_e32 v45, 0x50, v43
	ds_read_b128 v[66:69], v44
	ds_read_b128 v[98:101], v45
	v_xor_b32_e32 v44, 0x60, v42
	v_xor_b32_e32 v45, 0x60, v43
	ds_read_b128 v[70:73], v44
	ds_read_b128 v[102:105], v45
	v_xor_b32_e32 v44, 0x70, v42
	v_xor_b32_e32 v45, 0x70, v43
	ds_read_b128 v[74:77], v44
	ds_read_b128 v[106:109], v45
	s_waitcnt lgkmcnt(14)
	v_mfma_f32_16x16x4_f32 v[18:21], v78, v46, v[18:21]
	v_mfma_f32_16x16x4_f32 v[18:21], v79, v47, v[18:21]
	v_mfma_f32_16x16x4_f32 v[18:21], v80, v48, v[18:21]
	v_mfma_f32_16x16x4_f32 v[18:21], v81, v49, v[18:21]
	s_waitcnt lgkmcnt(12)
	v_mfma_f32_16x16x4_f32 v[18:21], v82, v50, v[18:21]
	v_mfma_f32_16x16x4_f32 v[18:21], v83, v51, v[18:21]
	v_mfma_f32_16x16x4_f32 v[18:21], v84, v52, v[18:21]
	v_mfma_f32_16x16x4_f32 v[18:21], v85, v53, v[18:21]
	s_waitcnt lgkmcnt(10)
	v_mfma_f32_16x16x4_f32 v[18:21], v86, v54, v[18:21]
	v_mfma_f32_16x16x4_f32 v[18:21], v87, v55, v[18:21]
	v_mfma_f32_16x16x4_f32 v[18:21], v88, v56, v[18:21]
	v_mfma_f32_16x16x4_f32 v[18:21], v89, v57, v[18:21]
	s_waitcnt lgkmcnt(8)
	v_mfma_f32_16x16x4_f32 v[18:21], v90, v58, v[18:21]
	v_mfma_f32_16x16x4_f32 v[18:21], v91, v59, v[18:21]
	v_mfma_f32_16x16x4_f32 v[18:21], v92, v60, v[18:21]
	v_mfma_f32_16x16x4_f32 v[18:21], v93, v61, v[18:21]
	s_waitcnt vmcnt(0)
	s_waitcnt lgkmcnt(0)
	s_barrier
; __device__ __forceinline__ void phase_row1(const Frame& F, int l) {
;     ...
;             const int fr = lane & 15, fq = lane >> 4, tile = w >> 1, nt = w & 1;
;             const float* wp = (const float*)(F.ws + WS_RWT) + ((size_t)l * NE + 16 * nt + fr) * D + 256 * fq;
;             const float* hp = H32 + (size_t)(chunk * 64 + 16 * tile + fr) * D + 256 * fq;
;             f32x4 c = {0.f, 0.f, 0.f, 0.f};
; #pragma unroll 16
;             for (int s4 = 0; s4 < 256; s4 += 4) { const f32x4 a = *(const f32x4*)(wp + s4), bq = *(const f32x4*)(hp + s4);
;                 c = __builtin_amdgcn_mfma_f32_16x16x4f32(a.x, bq.x, c, 0, 0, 0); c = __builtin_amdgcn_mfma_f32_16x16x4f32(a.y, bq.y, c, 0, 0, 0);
;                 c = __builtin_amdgcn_mfma_f32_16x16x4f32(a.z, bq.z, c, 0, 0, 0); c = __builtin_amdgcn_mfma_f32_16x16x4f32(a.w, bq.w, c, 0, 0, 0); }
; #pragma unroll
;             for (int j = 0; j < 4; ++j) { const int e = 16 * nt + 4 * fq + j; lg[(16 * tile + fr) * 33 + e] = c[j] + F.in[15][l * NE + e]; }
;         }
;         __syncthreads();
	ds_read_b128 v[46:49], v42 offset:49152
	ds_read_b128 v[78:81], v43 offset:49152
	v_xor_b32_e32 v44, 16, v42
	v_xor_b32_e32 v45, 16, v43
	ds_read_b128 v[50:53], v44 offset:49152
	ds_read_b128 v[82:85], v45 offset:49152
	v_xor_b32_e32 v44, 32, v42
	v_xor_b32_e32 v45, 32, v43
	ds_read_b128 v[54:57], v44 offset:49152
	ds_read_b128 v[86:89], v45 offset:49152
	v_xor_b32_e32 v44, 48, v42
	v_xor_b32_e32 v45, 48, v43
	ds_read_b128 v[58:61], v44 offset:49152
	ds_read_b128 v[90:93], v45 offset:49152
	s_waitcnt lgkmcnt(14)
	v_mfma_f32_16x16x4_f32 v[18:21], v94, v62, v[18:21]
	v_mfma_f32_16x16x4_f32 v[18:21], v95, v63, v[18:21]
	v_mfma_f32_16x16x4_f32 v[18:21], v96, v64, v[18:21]
	v_mfma_f32_16x16x4_f32 v[18:21], v97, v65, v[18:21]
	s_waitcnt lgkmcnt(12)
	v_mfma_f32_16x16x4_f32 v[18:21], v98, v66, v[18:21]
	v_mfma_f32_16x16x4_f32 v[18:21], v99, v67, v[18:21]
	v_mfma_f32_16x16x4_f32 v[18:21], v100, v68, v[18:21]
	v_mfma_f32_16x16x4_f32 v[18:21], v101, v69, v[18:21]
	s_waitcnt lgkmcnt(10)
	v_mfma_f32_16x16x4_f32 v[18:21], v102, v70, v[18:21]
	v_mfma_f32_16x16x4_f32 v[18:21], v103, v71, v[18:21]
	v_mfma_f32_16x16x4_f32 v[18:21], v104, v72, v[18:21]
	v_mfma_f32_16x16x4_f32 v[18:21], v105, v73, v[18:21]
	s_waitcnt lgkmcnt(8)
	v_mfma_f32_16x16x4_f32 v[18:21], v106, v74, v[18:21]
	v_mfma_f32_16x16x4_f32 v[18:21], v107, v75, v[18:21]
	v_mfma_f32_16x16x4_f32 v[18:21], v108, v76, v[18:21]
	v_mfma_f32_16x16x4_f32 v[18:21], v109, v77, v[18:21]
	v_xor_b32_e32 v44, 64, v42
	v_xor_b32_e32 v45, 64, v43
	ds_read_b128 v[62:65], v44 offset:49152
	ds_read_b128 v[94:97], v45 offset:49152
	v_xor_b32_e32 v44, 0x50, v42
	v_xor_b32_e32 v45, 0x50, v43
	ds_read_b128 v[66:69], v44 offset:49152
	ds_read_b128 v[98:101], v45 offset:49152
	v_xor_b32_e32 v44, 0x60, v42
	v_xor_b32_e32 v45, 0x60, v43
	ds_read_b128 v[70:73], v44 offset:49152
	ds_read_b128 v[102:105], v45 offset:49152
	v_xor_b32_e32 v44, 0x70, v42
	v_xor_b32_e32 v45, 0x70, v43
	ds_read_b128 v[74:77], v44 offset:49152
	ds_read_b128 v[106:109], v45 offset:49152
	s_waitcnt lgkmcnt(14)
	v_mfma_f32_16x16x4_f32 v[18:21], v78, v46, v[18:21]
	v_mfma_f32_16x16x4_f32 v[18:21], v79, v47, v[18:21]
	v_mfma_f32_16x16x4_f32 v[18:21], v80, v48, v[18:21]
	v_mfma_f32_16x16x4_f32 v[18:21], v81, v49, v[18:21]
	s_waitcnt lgkmcnt(12)
	v_mfma_f32_16x16x4_f32 v[18:21], v82, v50, v[18:21]
	v_mfma_f32_16x16x4_f32 v[18:21], v83, v51, v[18:21]
	v_mfma_f32_16x16x4_f32 v[18:21], v84, v52, v[18:21]
	v_mfma_f32_16x16x4_f32 v[18:21], v85, v53, v[18:21]
	s_waitcnt lgkmcnt(10)
	v_mfma_f32_16x16x4_f32 v[18:21], v86, v54, v[18:21]
	v_mfma_f32_16x16x4_f32 v[18:21], v87, v55, v[18:21]
	v_mfma_f32_16x16x4_f32 v[18:21], v88, v56, v[18:21]
	v_mfma_f32_16x16x4_f32 v[18:21], v89, v57, v[18:21]
	s_waitcnt lgkmcnt(8)
	v_mfma_f32_16x16x4_f32 v[18:21], v90, v58, v[18:21]
	v_mfma_f32_16x16x4_f32 v[18:21], v91, v59, v[18:21]
	v_mfma_f32_16x16x4_f32 v[18:21], v92, v60, v[18:21]
	v_mfma_f32_16x16x4_f32 v[18:21], v93, v61, v[18:21]
	s_waitcnt lgkmcnt(6)
	v_mfma_f32_16x16x4_f32 v[18:21], v94, v62, v[18:21]
	v_mfma_f32_16x16x4_f32 v[18:21], v95, v63, v[18:21]
	v_mfma_f32_16x16x4_f32 v[18:21], v96, v64, v[18:21]
	v_mfma_f32_16x16x4_f32 v[18:21], v97, v65, v[18:21]
	s_waitcnt lgkmcnt(4)
	v_mfma_f32_16x16x4_f32 v[18:21], v98, v66, v[18:21]
	v_mfma_f32_16x16x4_f32 v[18:21], v99, v67, v[18:21]
	v_mfma_f32_16x16x4_f32 v[18:21], v100, v68, v[18:21]
	v_mfma_f32_16x16x4_f32 v[18:21], v101, v69, v[18:21]
	s_waitcnt lgkmcnt(2)
	v_mfma_f32_16x16x4_f32 v[18:21], v102, v70, v[18:21]
	v_mfma_f32_16x16x4_f32 v[18:21], v103, v71, v[18:21]
	v_mfma_f32_16x16x4_f32 v[18:21], v104, v72, v[18:21]
	v_mfma_f32_16x16x4_f32 v[18:21], v105, v73, v[18:21]
	s_waitcnt lgkmcnt(0)
	v_mfma_f32_16x16x4_f32 v[18:21], v106, v74, v[18:21]
	v_mfma_f32_16x16x4_f32 v[18:21], v107, v75, v[18:21]
	v_mfma_f32_16x16x4_f32 v[18:21], v108, v76, v[18:21]
	v_mfma_f32_16x16x4_f32 v[18:21], v109, v77, v[18:21]
	global_load_dwordx4 v[22:25], v[130:131], off
	s_and_b64 vcc, exec, s[52:53]
	s_waitcnt vmcnt(0)
	s_nop 5
	v_pk_add_f32 v[18:19], v[18:19], v[22:23]
	ds_write2_b32 v155, v18, v19 offset1:1
	v_pk_add_f32 v[18:19], v[20:21], v[24:25]
	ds_write2_b32 v155, v18, v19 offset0:2 offset1:3
	s_waitcnt lgkmcnt(0)
	s_barrier
	s_cbranch_vccz .LBB0_2134
; __device__ __forceinline__ void phase_row1(const Frame& F, int l) {
;     ...
;         if (w == 0) {
;             const int row = chunk * 64 + lane;
;             float v[32];
; #pragma unroll
;             for (int e = 0; e < 32; ++e) v[e] = lg[lane * 33 + e];
;             float tv[4]; int ti[4];
; #pragma unroll
;             for (int r = 0; r < 4; ++r) { float bv = v[0]; int bi = 0;
; #pragma unroll
;                 for (int e = 1; e < 32; ++e) { const bool tk = v[e] > bv; bv = tk ? v[e] : bv; bi = tk ? e : bi; }
;                 tv[r] = bv; ti[r] = bi;
; #pragma unroll
;                 for (int e = 0; e < 32; ++e) v[e] = (e == bi) ? -INFINITY : v[e]; }
	ds_read2_b32 v[22:23], v154 offset0:8 offset1:9
	ds_read2_b32 v[26:27], v154 offset0:10 offset1:11
	ds_read2_b32 v[28:29], v154 offset0:12 offset1:13
	ds_read2_b32 v[30:31], v154 offset0:14 offset1:15
	ds_read2_b32 v[32:33], v154 offset0:16 offset1:17
	ds_read2_b32 v[34:35], v154 offset0:18 offset1:19
	ds_read2_b32 v[36:37], v154 offset0:20 offset1:21
	ds_read2_b32 v[38:39], v154 offset0:22 offset1:23
	ds_read2_b32 v[40:41], v154 offset0:2 offset1:3
	ds_read2_b32 v[42:43], v154 offset0:4 offset1:5
	ds_read2_b32 v[44:45], v154 offset0:6 offset1:7
	ds_read2_b32 v[46:47], v154 offset1:1
	ds_read2_b32 v[48:49], v154 offset0:24 offset1:25
	ds_read2_b32 v[50:51], v154 offset0:26 offset1:27
	ds_read2_b32 v[52:53], v154 offset0:28 offset1:29
	ds_read2_b32 v[20:21], v154 offset0:30 offset1:31
	s_waitcnt lgkmcnt(4)
	v_cmp_gt_f32_e32 vcc, v47, v46
	v_mov_b32_e32 v25, 0
	s_nop 0
	v_cndmask_b32_e32 v19, v46, v47, vcc
	v_cndmask_b32_e64 v18, 0, 1, vcc
	v_cmp_gt_f32_e32 vcc, v40, v19
	s_nop 1
	v_cndmask_b32_e32 v19, v19, v40, vcc
	v_cndmask_b32_e64 v18, v18, 2, vcc
	v_cmp_gt_f32_e32 vcc, v41, v19
	s_nop 1
	v_cndmask_b32_e32 v19, v19, v41, vcc
	v_cndmask_b32_e64 v18, v18, 3, vcc
	v_cmp_gt_f32_e32 vcc, v42, v19
	s_nop 1
	v_cndmask_b32_e32 v19, v19, v42, vcc
	v_cndmask_b32_e64 v18, v18, 4, vcc
	v_cmp_gt_f32_e32 vcc, v43, v19
	s_nop 1
	v_cndmask_b32_e32 v19, v19, v43, vcc
	v_cndmask_b32_e64 v18, v18, 5, vcc
	v_cmp_gt_f32_e32 vcc, v44, v19
	s_nop 1
	v_cndmask_b32_e32 v19, v19, v44, vcc
	v_cndmask_b32_e64 v18, v18, 6, vcc
	v_cmp_gt_f32_e32 vcc, v45, v19
	s_nop 1
	v_cndmask_b32_e32 v19, v19, v45, vcc
	v_cndmask_b32_e64 v18, v18, 7, vcc
	v_cmp_gt_f32_e32 vcc, v22, v19
	s_nop 1
	v_cndmask_b32_e32 v19, v19, v22, vcc
	v_cndmask_b32_e64 v18, v18, 8, vcc
	v_cmp_gt_f32_e32 vcc, v23, v19
	s_nop 1
	v_cndmask_b32_e32 v19, v19, v23, vcc
	v_cndmask_b32_e64 v18, v18, 9, vcc
	v_cmp_gt_f32_e32 vcc, v26, v19
	s_nop 1
	v_cndmask_b32_e32 v19, v19, v26, vcc
	v_cndmask_b32_e64 v18, v18, 10, vcc
	v_cmp_gt_f32_e32 vcc, v27, v19
	s_nop 1
	v_cndmask_b32_e32 v19, v19, v27, vcc
	v_cndmask_b32_e64 v18, v18, 11, vcc
	v_cmp_gt_f32_e32 vcc, v28, v19
	s_nop 1
	v_cndmask_b32_e32 v19, v19, v28, vcc
	v_cndmask_b32_e64 v18, v18, 12, vcc
	v_cmp_gt_f32_e32 vcc, v29, v19
	s_nop 1
	v_cndmask_b32_e32 v19, v19, v29, vcc
	v_cndmask_b32_e64 v18, v18, 13, vcc
	v_cmp_gt_f32_e32 vcc, v30, v19
	s_nop 1
	v_cndmask_b32_e32 v19, v19, v30, vcc
	v_cndmask_b32_e64 v18, v18, 14, vcc
	v_cmp_gt_f32_e32 vcc, v31, v19
	s_nop 1
	v_cndmask_b32_e32 v19, v19, v31, vcc
	v_cndmask_b32_e64 v18, v18, 15, vcc
	v_cmp_gt_f32_e32 vcc, v32, v19
	s_nop 1
	v_cndmask_b32_e32 v19, v19, v32, vcc
	v_cndmask_b32_e64 v18, v18, 16, vcc
	v_cmp_gt_f32_e32 vcc, v33, v19
	s_nop 1
	v_cndmask_b32_e32 v19, v19, v33, vcc
	v_cndmask_b32_e64 v18, v18, 17, vcc
	v_cmp_gt_f32_e32 vcc, v34, v19
	s_nop 1
	v_cndmask_b32_e32 v19, v19, v34, vcc
	v_cndmask_b32_e64 v18, v18, 18, vcc
	v_cmp_gt_f32_e32 vcc, v35, v19
	s_nop 1
	v_cndmask_b32_e32 v19, v19, v35, vcc
	v_cndmask_b32_e64 v18, v18, 19, vcc
	v_cmp_gt_f32_e32 vcc, v36, v19
	s_nop 1
	v_cndmask_b32_e32 v19, v19, v36, vcc
	v_cndmask_b32_e64 v18, v18, 20, vcc
	v_cmp_gt_f32_e32 vcc, v37, v19
	s_nop 1
	v_cndmask_b32_e32 v19, v19, v37, vcc
	v_cndmask_b32_e64 v18, v18, 21, vcc
	v_cmp_gt_f32_e32 vcc, v38, v19
	s_nop 1
	v_cndmask_b32_e32 v19, v19, v38, vcc
	v_cndmask_b32_e64 v18, v18, 22, vcc
	v_cmp_gt_f32_e32 vcc, v39, v19
	s_nop 1
	v_cndmask_b32_e32 v19, v19, v39, vcc
	v_cndmask_b32_e64 v18, v18, 23, vcc
	s_waitcnt lgkmcnt(3)
	v_cmp_gt_f32_e32 vcc, v48, v19
	s_nop 1
	v_cndmask_b32_e32 v19, v19, v48, vcc
	v_cndmask_b32_e64 v18, v18, 24, vcc
	v_cmp_gt_f32_e32 vcc, v49, v19
	s_nop 1
	v_cndmask_b32_e32 v19, v19, v49, vcc
	v_cndmask_b32_e64 v18, v18, 25, vcc
	s_waitcnt lgkmcnt(2)
	v_cmp_gt_f32_e32 vcc, v50, v19
	s_nop 1
	v_cndmask_b32_e32 v19, v19, v50, vcc
	v_cndmask_b32_e64 v18, v18, 26, vcc
	v_cmp_gt_f32_e32 vcc, v51, v19
	s_nop 1
	v_cndmask_b32_e32 v19, v19, v51, vcc
	v_cndmask_b32_e64 v18, v18, 27, vcc
	s_waitcnt lgkmcnt(1)
	v_cmp_gt_f32_e32 vcc, v52, v19
	s_nop 1
	v_cndmask_b32_e32 v19, v19, v52, vcc
	v_cndmask_b32_e64 v18, v18, 28, vcc
	v_cmp_gt_f32_e32 vcc, v53, v19
	s_nop 1
	v_cndmask_b32_e32 v19, v19, v53, vcc
	v_cndmask_b32_e64 v18, v18, 29, vcc
	s_waitcnt lgkmcnt(0)
; __device__ __forceinline__ void phase_row1(const Frame& F, int l) {
;     ...
;             float tv[4]; int ti[4];
; #pragma unroll
;             for (int r = 0; r < 4; ++r) { float bv = v[0]; int bi = 0;
; #pragma unroll
;                 for (int e = 1; e < 32; ++e) { const bool tk = v[e] > bv; bv = tk ? v[e] : bv; bi = tk ? e : bi; }
;                 tv[r] = bv; ti[r] = bi;
; #pragma unroll
;                 for (int e = 0; e < 32; ++e) v[e] = (e == bi) ? -INFINITY : v[e]; }
	v_cmp_gt_f32_e32 vcc, v20, v19
	s_nop 1
	v_cndmask_b32_e32 v19, v19, v20, vcc
	v_cndmask_b32_e64 v18, v18, 30, vcc
	v_cmp_gt_f32_e32 vcc, v21, v19
	s_nop 1
	v_cndmask_b32_e64 v18, v18, 31, vcc
	v_cmp_ne_u32_e64 s[44:45], 0, v18
	s_nop 1
	v_cndmask_b32_e64 v24, v237, v46, s[44:45]
	v_cmp_ne_u32_e64 s[44:45], 1, v18
	s_nop 1
	v_cndmask_b32_e64 v46, v237, v47, s[44:45]
	v_cmp_ne_u32_e64 s[44:45], 2, v18
	s_nop 1
	v_cndmask_b32_e64 v40, v237, v40, s[44:45]
	v_cmp_ne_u32_e64 s[44:45], 3, v18
	s_nop 1
	v_cndmask_b32_e64 v41, v237, v41, s[44:45]
	v_cmp_ne_u32_e64 s[44:45], 4, v18
	s_nop 1
	v_cndmask_b32_e64 v42, v237, v42, s[44:45]
	v_cmp_ne_u32_e64 s[44:45], 5, v18
	s_nop 1
	v_cndmask_b32_e64 v43, v237, v43, s[44:45]
	v_cmp_ne_u32_e64 s[44:45], 6, v18
	s_nop 1
	v_cndmask_b32_e64 v44, v237, v44, s[44:45]
	v_cmp_ne_u32_e64 s[44:45], 7, v18
	s_nop 1
	v_cndmask_b32_e64 v45, v237, v45, s[44:45]
	v_cmp_ne_u32_e64 s[44:45], 8, v18
	s_nop 1
	v_cndmask_b32_e64 v22, v237, v22, s[44:45]
	v_cmp_ne_u32_e64 s[44:45], 9, v18
	s_nop 1
	v_cndmask_b32_e64 v47, v237, v23, s[44:45]
	v_cmp_ne_u32_e64 s[44:45], 10, v18
	s_nop 1
	v_cndmask_b32_e64 v26, v237, v26, s[44:45]
	v_cmp_ne_u32_e64 s[44:45], 11, v18
	s_nop 1
	v_cndmask_b32_e64 v54, v237, v27, s[44:45]
	v_cmp_ne_u32_e64 s[44:45], 12, v18
	s_nop 1
	v_cndmask_b32_e64 v28, v237, v28, s[44:45]
	v_cmp_ne_u32_e64 s[44:45], 13, v18
	s_nop 1
	v_cndmask_b32_e64 v29, v237, v29, s[44:45]
	v_cmp_ne_u32_e64 s[44:45], 14, v18
	s_nop 1
	v_cndmask_b32_e64 v30, v237, v30, s[44:45]
	v_cmp_ne_u32_e64 s[44:45], 15, v18
	s_nop 1
	v_cndmask_b32_e64 v31, v237, v31, s[44:45]
	v_cmp_ne_u32_e64 s[44:45], 16, v18
	s_nop 1
	v_cndmask_b32_e64 v32, v237, v32, s[44:45]
	v_cmp_ne_u32_e64 s[44:45], 17, v18
	s_nop 1
	v_cndmask_b32_e64 v33, v237, v33, s[44:45]
	v_cmp_ne_u32_e64 s[44:45], 18, v18
	s_nop 1
	v_cndmask_b32_e64 v34, v237, v34, s[44:45]
	v_cmp_ne_u32_e64 s[44:45], 19, v18
	s_nop 1
	v_cndmask_b32_e64 v35, v237, v35, s[44:45]
	v_cmp_ne_u32_e64 s[44:45], 20, v18
	s_nop 1
	v_cndmask_b32_e64 v36, v237, v36, s[44:45]
	v_cmp_ne_u32_e64 s[44:45], 21, v18
	s_nop 1
	v_cndmask_b32_e64 v37, v237, v37, s[44:45]
	v_cmp_ne_u32_e64 s[44:45], 22, v18
	s_nop 1
	v_cndmask_b32_e64 v38, v237, v38, s[44:45]
	v_cmp_ne_u32_e64 s[44:45], 23, v18
	s_nop 1
	v_cndmask_b32_e64 v39, v237, v39, s[44:45]
	v_cmp_ne_u32_e64 s[44:45], 24, v18
	s_nop 1
	v_cndmask_b32_e64 v48, v237, v48, s[44:45]
	v_cmp_ne_u32_e64 s[44:45], 25, v18
	s_nop 1
	v_cndmask_b32_e64 v49, v237, v49, s[44:45]
	v_cmp_ne_u32_e64 s[44:45], 26, v18
	s_nop 1
	v_cndmask_b32_e64 v50, v237, v50, s[44:45]
	v_cmp_ne_u32_e64 s[44:45], 27, v18
	s_nop 1
	v_cndmask_b32_e64 v51, v237, v51, s[44:45]
	v_cmp_ne_u32_e64 s[44:45], 28, v18
	s_nop 1
	v_cndmask_b32_e64 v52, v237, v52, s[44:45]
	v_cmp_ne_u32_e64 s[44:45], 29, v18
	s_nop 1
	v_cndmask_b32_e64 v53, v237, v53, s[44:45]
	v_cmp_ne_u32_e64 s[44:45], 30, v18
	s_nop 1
	v_cndmask_b32_e64 v55, v237, v20, s[44:45]
	v_cmp_ne_u32_e64 s[44:45], 31, v18
	s_nop 1
	v_cndmask_b32_e64 v23, v237, v21, s[44:45]
	v_cmp_gt_f32_e64 s[44:45], v46, v24
	s_nop 1
	v_cndmask_b32_e64 v27, v24, v46, s[44:45]
	v_cndmask_b32_e64 v20, 0, 1, s[44:45]
	v_cmp_gt_f32_e64 s[44:45], v40, v27
	s_nop 1
	v_cndmask_b32_e64 v27, v27, v40, s[44:45]
	v_cndmask_b32_e64 v20, v20, 2, s[44:45]
	v_cmp_gt_f32_e64 s[44:45], v41, v27
	s_nop 1
	v_cndmask_b32_e64 v27, v27, v41, s[44:45]
	v_cndmask_b32_e64 v20, v20, 3, s[44:45]
	v_cmp_gt_f32_e64 s[44:45], v42, v27
	s_nop 1
	v_cndmask_b32_e64 v27, v27, v42, s[44:45]
	v_cndmask_b32_e64 v20, v20, 4, s[44:45]
	v_cmp_gt_f32_e64 s[44:45], v43, v27
	s_nop 1
	v_cndmask_b32_e64 v27, v27, v43, s[44:45]
	v_cndmask_b32_e64 v20, v20, 5, s[44:45]
	v_cmp_gt_f32_e64 s[44:45], v44, v27
	s_nop 1
	v_cndmask_b32_e64 v27, v27, v44, s[44:45]
	v_cndmask_b32_e64 v20, v20, 6, s[44:45]
	v_cmp_gt_f32_e64 s[44:45], v45, v27
	s_nop 1
	v_cndmask_b32_e64 v27, v27, v45, s[44:45]
	v_cndmask_b32_e64 v20, v20, 7, s[44:45]
	v_cmp_gt_f32_e64 s[44:45], v22, v27
	s_nop 1
	v_cndmask_b32_e64 v27, v27, v22, s[44:45]
	v_cndmask_b32_e64 v20, v20, 8, s[44:45]
	v_cmp_gt_f32_e64 s[44:45], v47, v27
	s_nop 1
	v_cndmask_b32_e64 v27, v27, v47, s[44:45]
	v_cndmask_b32_e64 v20, v20, 9, s[44:45]
	v_cmp_gt_f32_e64 s[44:45], v26, v27
	s_nop 1
	v_cndmask_b32_e64 v27, v27, v26, s[44:45]
	v_cndmask_b32_e64 v20, v20, 10, s[44:45]
	v_cmp_gt_f32_e64 s[44:45], v54, v27
	s_nop 1
	v_cndmask_b32_e64 v27, v27, v54, s[44:45]
	v_cndmask_b32_e64 v20, v20, 11, s[44:45]
	v_cmp_gt_f32_e64 s[44:45], v28, v27
	s_nop 1
	v_cndmask_b32_e64 v27, v27, v28, s[44:45]
	v_cndmask_b32_e64 v20, v20, 12, s[44:45]
	v_cmp_gt_f32_e64 s[44:45], v29, v27
	s_nop 1
	v_cndmask_b32_e64 v27, v27, v29, s[44:45]
	v_cndmask_b32_e64 v20, v20, 13, s[44:45]
	v_cmp_gt_f32_e64 s[44:45], v30, v27
	s_nop 1
	v_cndmask_b32_e64 v27, v27, v30, s[44:45]
	v_cndmask_b32_e64 v20, v20, 14, s[44:45]
	v_cmp_gt_f32_e64 s[44:45], v31, v27
	s_nop 1
	v_cndmask_b32_e64 v27, v27, v31, s[44:45]
	v_cndmask_b32_e64 v20, v20, 15, s[44:45]
	v_cmp_gt_f32_e64 s[44:45], v32, v27
	s_nop 1
	v_cndmask_b32_e64 v27, v27, v32, s[44:45]
	v_cndmask_b32_e64 v20, v20, 16, s[44:45]
	v_cmp_gt_f32_e64 s[44:45], v33, v27
	s_nop 1
	v_cndmask_b32_e64 v27, v27, v33, s[44:45]
	v_cndmask_b32_e64 v20, v20, 17, s[44:45]
	v_cmp_gt_f32_e64 s[44:45], v34, v27
	s_nop 1
	v_cndmask_b32_e64 v27, v27, v34, s[44:45]
	v_cndmask_b32_e64 v20, v20, 18, s[44:45]
	v_cmp_gt_f32_e64 s[44:45], v35, v27
	s_nop 1
	v_cndmask_b32_e64 v27, v27, v35, s[44:45]
	v_cndmask_b32_e64 v20, v20, 19, s[44:45]
	v_cmp_gt_f32_e64 s[44:45], v36, v27
	s_nop 1
	v_cndmask_b32_e64 v27, v27, v36, s[44:45]
	v_cndmask_b32_e64 v20, v20, 20, s[44:45]
; __device__ __forceinline__ void phase_row1(const Frame& F, int l) {
;     ...
;             float tv[4]; int ti[4];
; #pragma unroll
;             for (int r = 0; r < 4; ++r) { float bv = v[0]; int bi = 0;
; #pragma unroll
;                 for (int e = 1; e < 32; ++e) { const bool tk = v[e] > bv; bv = tk ? v[e] : bv; bi = tk ? e : bi; }
;                 tv[r] = bv; ti[r] = bi;
; #pragma unroll
;                 for (int e = 0; e < 32; ++e) v[e] = (e == bi) ? -INFINITY : v[e]; }
	v_cmp_gt_f32_e64 s[44:45], v37, v27
	s_nop 1
	v_cndmask_b32_e64 v27, v27, v37, s[44:45]
	v_cndmask_b32_e64 v20, v20, 21, s[44:45]
	v_cmp_gt_f32_e64 s[44:45], v38, v27
	s_nop 1
	v_cndmask_b32_e64 v27, v27, v38, s[44:45]
	v_cndmask_b32_e64 v20, v20, 22, s[44:45]
	v_cmp_gt_f32_e64 s[44:45], v39, v27
	s_nop 1
	v_cndmask_b32_e64 v27, v27, v39, s[44:45]
	v_cndmask_b32_e64 v20, v20, 23, s[44:45]
	v_cmp_gt_f32_e64 s[44:45], v48, v27
	s_nop 1
	v_cndmask_b32_e64 v27, v27, v48, s[44:45]
	v_cndmask_b32_e64 v20, v20, 24, s[44:45]
	v_cmp_gt_f32_e64 s[44:45], v49, v27
	s_nop 1
	v_cndmask_b32_e64 v27, v27, v49, s[44:45]
	v_cndmask_b32_e64 v20, v20, 25, s[44:45]
	v_cmp_gt_f32_e64 s[44:45], v50, v27
	s_nop 1
	v_cndmask_b32_e64 v27, v27, v50, s[44:45]
	v_cndmask_b32_e64 v20, v20, 26, s[44:45]
	v_cmp_gt_f32_e64 s[44:45], v51, v27
	s_nop 1
	v_cndmask_b32_e64 v27, v27, v51, s[44:45]
	v_cndmask_b32_e64 v20, v20, 27, s[44:45]
	v_cmp_gt_f32_e64 s[44:45], v52, v27
	s_nop 1
	v_cndmask_b32_e64 v27, v27, v52, s[44:45]
	v_cndmask_b32_e64 v20, v20, 28, s[44:45]
	v_cmp_gt_f32_e64 s[44:45], v53, v27
	s_nop 1
	v_cndmask_b32_e64 v27, v27, v53, s[44:45]
	v_cndmask_b32_e64 v20, v20, 29, s[44:45]
	v_cmp_gt_f32_e64 s[44:45], v55, v27
	s_nop 1
	v_cndmask_b32_e64 v27, v27, v55, s[44:45]
	v_cndmask_b32_e64 v20, v20, 30, s[44:45]
	v_cmp_gt_f32_e64 s[44:45], v23, v27
	s_nop 1
	v_cndmask_b32_e64 v20, v20, 31, s[44:45]
	v_cmp_ne_u32_e64 s[46:47], 0, v20
	s_nop 1
	v_cndmask_b32_e64 v24, v237, v24, s[46:47]
	v_cmp_ne_u32_e64 s[46:47], 1, v20
	s_nop 1
	v_cndmask_b32_e64 v46, v237, v46, s[46:47]
	v_cmp_ne_u32_e64 s[46:47], 2, v20
	s_nop 1
	v_cndmask_b32_e64 v40, v237, v40, s[46:47]
	v_cmp_ne_u32_e64 s[46:47], 3, v20
	s_nop 1
	v_cndmask_b32_e64 v41, v237, v41, s[46:47]
	v_cmp_ne_u32_e64 s[46:47], 4, v20
	s_nop 1
	v_cndmask_b32_e64 v42, v237, v42, s[46:47]
	v_cmp_ne_u32_e64 s[46:47], 5, v20
	s_nop 1
	v_cndmask_b32_e64 v43, v237, v43, s[46:47]
	v_cmp_ne_u32_e64 s[46:47], 6, v20
	s_nop 1
	v_cndmask_b32_e64 v44, v237, v44, s[46:47]
	v_cmp_ne_u32_e64 s[46:47], 7, v20
	s_nop 1
	v_cndmask_b32_e64 v45, v237, v45, s[46:47]
	v_cmp_ne_u32_e64 s[46:47], 8, v20
	s_nop 1
	v_cndmask_b32_e64 v56, v237, v22, s[46:47]
	v_cmp_ne_u32_e64 s[46:47], 9, v20
	s_nop 1
	v_cndmask_b32_e64 v47, v237, v47, s[46:47]
	v_cmp_ne_u32_e64 s[46:47], 10, v20
	s_nop 1
	v_cndmask_b32_e64 v26, v237, v26, s[46:47]
	v_cmp_ne_u32_e64 s[46:47], 11, v20
	s_nop 1
	v_cndmask_b32_e64 v54, v237, v54, s[46:47]
	v_cmp_ne_u32_e64 s[46:47], 12, v20
	s_nop 1
	v_cndmask_b32_e64 v28, v237, v28, s[46:47]
	v_cmp_ne_u32_e64 s[46:47], 13, v20
	s_nop 1
	v_cndmask_b32_e64 v57, v237, v29, s[46:47]
	v_cmp_ne_u32_e64 s[46:47], 14, v20
	s_nop 1
	v_cndmask_b32_e64 v30, v237, v30, s[46:47]
	v_cmp_ne_u32_e64 s[46:47], 15, v20
	s_nop 1
	v_cndmask_b32_e64 v58, v237, v31, s[46:47]
	v_cmp_ne_u32_e64 s[46:47], 16, v20
	s_nop 1
	v_cndmask_b32_e64 v32, v237, v32, s[46:47]
	v_cmp_ne_u32_e64 s[46:47], 17, v20
	s_nop 1
	v_cndmask_b32_e64 v33, v237, v33, s[46:47]
	v_cmp_ne_u32_e64 s[46:47], 18, v20
	s_nop 1
	v_cndmask_b32_e64 v34, v237, v34, s[46:47]
	v_cmp_ne_u32_e64 s[46:47], 19, v20
	s_nop 1
	v_cndmask_b32_e64 v35, v237, v35, s[46:47]
	v_cmp_ne_u32_e64 s[46:47], 20, v20
	s_nop 1
	v_cndmask_b32_e64 v36, v237, v36, s[46:47]
	v_cmp_ne_u32_e64 s[46:47], 21, v20
	s_nop 1
	v_cndmask_b32_e64 v37, v237, v37, s[46:47]
	v_cmp_ne_u32_e64 s[46:47], 22, v20
	s_nop 1
	v_cndmask_b32_e64 v38, v237, v38, s[46:47]
	v_cmp_ne_u32_e64 s[46:47], 23, v20
	s_nop 1
	v_cndmask_b32_e64 v39, v237, v39, s[46:47]
	v_cmp_ne_u32_e64 s[46:47], 24, v20
	s_nop 1
	v_cndmask_b32_e64 v48, v237, v48, s[46:47]
	v_cmp_ne_u32_e64 s[46:47], 25, v20
	s_nop 1
	v_cndmask_b32_e64 v49, v237, v49, s[46:47]
	v_cmp_ne_u32_e64 s[46:47], 26, v20
	s_nop 1
	v_cndmask_b32_e64 v50, v237, v50, s[46:47]
	v_cmp_ne_u32_e64 s[46:47], 27, v20
	s_nop 1
	v_cndmask_b32_e64 v51, v237, v51, s[46:47]
	v_cmp_ne_u32_e64 s[46:47], 28, v20
	s_nop 1
	v_cndmask_b32_e64 v52, v237, v52, s[46:47]
	v_cmp_ne_u32_e64 s[46:47], 29, v20
	s_nop 1
	v_cndmask_b32_e64 v53, v237, v53, s[46:47]
	v_cmp_ne_u32_e64 s[46:47], 30, v20
	s_nop 1
	v_cndmask_b32_e64 v55, v237, v55, s[46:47]
	v_cmp_ne_u32_e64 s[46:47], 31, v20
	s_nop 1
	v_cndmask_b32_e64 v29, v237, v23, s[46:47]
	v_cmp_gt_f32_e64 s[46:47], v46, v24
	s_nop 1
	v_cndmask_b32_e64 v31, v24, v46, s[46:47]
	v_cndmask_b32_e64 v22, 0, 1, s[46:47]
	v_cmp_gt_f32_e64 s[46:47], v40, v31
	s_nop 1
	v_cndmask_b32_e64 v31, v31, v40, s[46:47]
	v_cndmask_b32_e64 v22, v22, 2, s[46:47]
	v_cmp_gt_f32_e64 s[46:47], v41, v31
	s_nop 1
	v_cndmask_b32_e64 v31, v31, v41, s[46:47]
	v_cndmask_b32_e64 v22, v22, 3, s[46:47]
	v_cmp_gt_f32_e64 s[46:47], v42, v31
	s_nop 1
	v_cndmask_b32_e64 v31, v31, v42, s[46:47]
	v_cndmask_b32_e64 v22, v22, 4, s[46:47]
	v_cmp_gt_f32_e64 s[46:47], v43, v31
	s_nop 1
	v_cndmask_b32_e64 v31, v31, v43, s[46:47]
	v_cndmask_b32_e64 v22, v22, 5, s[46:47]
	v_cmp_gt_f32_e64 s[46:47], v44, v31
	s_nop 1
	v_cndmask_b32_e64 v31, v31, v44, s[46:47]
	v_cndmask_b32_e64 v22, v22, 6, s[46:47]
	v_cmp_gt_f32_e64 s[46:47], v45, v31
	s_nop 1
	v_cndmask_b32_e64 v31, v31, v45, s[46:47]
	v_cndmask_b32_e64 v22, v22, 7, s[46:47]
	v_cmp_gt_f32_e64 s[46:47], v56, v31
	s_nop 1
	v_cndmask_b32_e64 v31, v31, v56, s[46:47]
	v_cndmask_b32_e64 v22, v22, 8, s[46:47]
	v_cmp_gt_f32_e64 s[46:47], v47, v31
	s_nop 1
	v_cndmask_b32_e64 v31, v31, v47, s[46:47]
	v_cndmask_b32_e64 v22, v22, 9, s[46:47]
	v_cmp_gt_f32_e64 s[46:47], v26, v31
	s_nop 1
	v_cndmask_b32_e64 v31, v31, v26, s[46:47]
	v_cndmask_b32_e64 v22, v22, 10, s[46:47]
	v_cmp_gt_f32_e64 s[46:47], v54, v31
	s_nop 1
	v_cndmask_b32_e64 v31, v31, v54, s[46:47]
; __device__ __forceinline__ void phase_row1(const Frame& F, int l) {
;     ...
;             float tv[4]; int ti[4];
; #pragma unroll
;             for (int r = 0; r < 4; ++r) { float bv = v[0]; int bi = 0;
; #pragma unroll
;                 for (int e = 1; e < 32; ++e) { const bool tk = v[e] > bv; bv = tk ? v[e] : bv; bi = tk ? e : bi; }
;                 tv[r] = bv; ti[r] = bi;
; #pragma unroll
;                 for (int e = 0; e < 32; ++e) v[e] = (e == bi) ? -INFINITY : v[e]; }
	v_cndmask_b32_e64 v22, v22, 11, s[46:47]
	v_cmp_gt_f32_e64 s[46:47], v28, v31
	s_nop 1
	v_cndmask_b32_e64 v31, v31, v28, s[46:47]
	v_cndmask_b32_e64 v22, v22, 12, s[46:47]
	v_cmp_gt_f32_e64 s[46:47], v57, v31
	s_nop 1
	v_cndmask_b32_e64 v31, v31, v57, s[46:47]
	v_cndmask_b32_e64 v22, v22, 13, s[46:47]
	v_cmp_gt_f32_e64 s[46:47], v30, v31
	s_nop 1
	v_cndmask_b32_e64 v31, v31, v30, s[46:47]
	v_cndmask_b32_e64 v22, v22, 14, s[46:47]
	v_cmp_gt_f32_e64 s[46:47], v58, v31
	s_nop 1
	v_cndmask_b32_e64 v31, v31, v58, s[46:47]
	v_cndmask_b32_e64 v22, v22, 15, s[46:47]
	v_cmp_gt_f32_e64 s[46:47], v32, v31
	s_nop 1
	v_cndmask_b32_e64 v31, v31, v32, s[46:47]
	v_cndmask_b32_e64 v22, v22, 16, s[46:47]
	v_cmp_gt_f32_e64 s[46:47], v33, v31
	s_nop 1
	v_cndmask_b32_e64 v31, v31, v33, s[46:47]
	v_cndmask_b32_e64 v22, v22, 17, s[46:47]
	v_cmp_gt_f32_e64 s[46:47], v34, v31
	s_nop 1
	v_cndmask_b32_e64 v31, v31, v34, s[46:47]
	v_cndmask_b32_e64 v22, v22, 18, s[46:47]
	v_cmp_gt_f32_e64 s[46:47], v35, v31
	s_nop 1
	v_cndmask_b32_e64 v31, v31, v35, s[46:47]
	v_cndmask_b32_e64 v22, v22, 19, s[46:47]
	v_cmp_gt_f32_e64 s[46:47], v36, v31
	s_nop 1
	v_cndmask_b32_e64 v31, v31, v36, s[46:47]
	v_cndmask_b32_e64 v22, v22, 20, s[46:47]
	v_cmp_gt_f32_e64 s[46:47], v37, v31
	s_nop 1
	v_cndmask_b32_e64 v31, v31, v37, s[46:47]
	v_cndmask_b32_e64 v22, v22, 21, s[46:47]
	v_cmp_gt_f32_e64 s[46:47], v38, v31
	s_nop 1
	v_cndmask_b32_e64 v31, v31, v38, s[46:47]
	v_cndmask_b32_e64 v22, v22, 22, s[46:47]
	v_cmp_gt_f32_e64 s[46:47], v39, v31
	s_nop 1
	v_cndmask_b32_e64 v31, v31, v39, s[46:47]
	v_cndmask_b32_e64 v22, v22, 23, s[46:47]
	v_cmp_gt_f32_e64 s[46:47], v48, v31
	s_nop 1
	v_cndmask_b32_e64 v31, v31, v48, s[46:47]
	v_cndmask_b32_e64 v22, v22, 24, s[46:47]
	v_cmp_gt_f32_e64 s[46:47], v49, v31
	s_nop 1
	v_cndmask_b32_e64 v31, v31, v49, s[46:47]
	v_cndmask_b32_e64 v22, v22, 25, s[46:47]
	v_cmp_gt_f32_e64 s[46:47], v50, v31
	s_nop 1
	v_cndmask_b32_e64 v31, v31, v50, s[46:47]
	v_cndmask_b32_e64 v22, v22, 26, s[46:47]
	v_cmp_gt_f32_e64 s[46:47], v51, v31
	s_nop 1
	v_cndmask_b32_e64 v31, v31, v51, s[46:47]
	v_cndmask_b32_e64 v22, v22, 27, s[46:47]
	v_cmp_gt_f32_e64 s[46:47], v52, v31
	s_nop 1
	v_cndmask_b32_e64 v31, v31, v52, s[46:47]
	v_cndmask_b32_e64 v22, v22, 28, s[46:47]
	v_cmp_gt_f32_e64 s[46:47], v53, v31
	s_nop 1
	v_cndmask_b32_e64 v31, v31, v53, s[46:47]
	v_cndmask_b32_e64 v22, v22, 29, s[46:47]
	v_cmp_gt_f32_e64 s[46:47], v55, v31
	s_nop 1
	v_cndmask_b32_e64 v31, v31, v55, s[46:47]
	v_cndmask_b32_e64 v22, v22, 30, s[46:47]
	v_cmp_gt_f32_e64 s[46:47], v29, v31
	s_nop 1
	v_cndmask_b32_e64 v22, v22, 31, s[46:47]
	v_cmp_ne_u32_e64 s[48:49], 0, v22
	s_nop 1
	v_cndmask_b32_e64 v24, v237, v24, s[48:49]
	v_cmp_ne_u32_e64 s[48:49], 1, v22
	s_nop 1
	v_cndmask_b32_e64 v46, v237, v46, s[48:49]
	v_cmp_ne_u32_e64 s[48:49], 2, v22
	s_nop 1
	v_cndmask_b32_e64 v40, v237, v40, s[48:49]
	v_cmp_ne_u32_e64 s[48:49], 3, v22
	s_nop 1
	v_cndmask_b32_e64 v41, v237, v41, s[48:49]
	v_cmp_ne_u32_e64 s[48:49], 4, v22
	s_nop 1
	v_cndmask_b32_e64 v42, v237, v42, s[48:49]
	v_cmp_ne_u32_e64 s[48:49], 5, v22
	s_nop 1
	v_cndmask_b32_e64 v43, v237, v43, s[48:49]
	v_cmp_ne_u32_e64 s[48:49], 6, v22
	s_nop 1
	v_cndmask_b32_e64 v44, v237, v44, s[48:49]
	v_cmp_ne_u32_e64 s[48:49], 7, v22
	s_nop 1
	v_cndmask_b32_e64 v45, v237, v45, s[48:49]
	v_cmp_ne_u32_e64 s[48:49], 8, v22
	s_nop 1
	v_cndmask_b32_e64 v56, v237, v56, s[48:49]
	v_cmp_ne_u32_e64 s[48:49], 9, v22
	s_nop 1
	v_cndmask_b32_e64 v47, v237, v47, s[48:49]
	v_cmp_ne_u32_e64 s[48:49], 10, v22
	s_nop 1
	v_cndmask_b32_e64 v26, v237, v26, s[48:49]
	v_cmp_ne_u32_e64 s[48:49], 11, v22
	s_nop 1
	v_cndmask_b32_e64 v54, v237, v54, s[48:49]
	v_cmp_ne_u32_e64 s[48:49], 12, v22
	s_nop 1
	v_cndmask_b32_e64 v28, v237, v28, s[48:49]
	v_cmp_ne_u32_e64 s[48:49], 13, v22
	s_nop 1
	v_cndmask_b32_e64 v57, v237, v57, s[48:49]
	v_cmp_ne_u32_e64 s[48:49], 14, v22
	s_nop 1
	v_cndmask_b32_e64 v30, v237, v30, s[48:49]
	v_cmp_ne_u32_e64 s[48:49], 15, v22
	s_nop 1
	v_cndmask_b32_e64 v58, v237, v58, s[48:49]
	v_cmp_ne_u32_e64 s[48:49], 16, v22
	s_nop 1
	v_cndmask_b32_e64 v59, v237, v32, s[48:49]
	v_cmp_ne_u32_e64 s[48:49], 17, v22
	s_nop 1
	v_cndmask_b32_e64 v60, v237, v33, s[48:49]
	v_cmp_ne_u32_e64 s[48:49], 18, v22
	s_nop 1
	v_cndmask_b32_e64 v34, v237, v34, s[48:49]
	v_cmp_ne_u32_e64 s[48:49], 19, v22
	s_nop 1
	v_cndmask_b32_e64 v61, v237, v35, s[48:49]
	v_cmp_ne_u32_e64 s[48:49], 20, v22
	s_nop 1
	v_cndmask_b32_e64 v62, v237, v36, s[48:49]
	v_cmp_ne_u32_e64 s[48:49], 21, v22
	s_nop 1
	v_cndmask_b32_e64 v63, v237, v37, s[48:49]
	v_cmp_ne_u32_e64 s[48:49], 22, v22
	s_nop 1
	v_cndmask_b32_e64 v38, v237, v38, s[48:49]
	v_cmp_ne_u32_e64 s[48:49], 23, v22
	s_nop 1
	v_cndmask_b32_e64 v39, v237, v39, s[48:49]
	v_cmp_ne_u32_e64 s[48:49], 24, v22
	s_nop 1
	v_cndmask_b32_e64 v48, v237, v48, s[48:49]
	v_cmp_ne_u32_e64 s[48:49], 25, v22
	s_nop 1
	v_cndmask_b32_e64 v49, v237, v49, s[48:49]
	v_cmp_ne_u32_e64 s[48:49], 26, v22
	s_nop 1
	v_cndmask_b32_e64 v50, v237, v50, s[48:49]
	v_cmp_ne_u32_e64 s[48:49], 27, v22
	s_nop 1
	v_cndmask_b32_e64 v51, v237, v51, s[48:49]
	v_cmp_ne_u32_e64 s[48:49], 28, v22
; #define LAS __attribute__((address_space(3)))
; #define LDS_WAIT() asm volatile("s_waitcnt lgkmcnt(0)" ::: "memory")
; __device__ __forceinline__ void phase_row1(const Frame& F, int l) {
;     ...
;             float tv[4]; int ti[4];
; #pragma unroll
;             for (int r = 0; r < 4; ++r) { float bv = v[0]; int bi = 0;
; #pragma unroll
;                 for (int e = 1; e < 32; ++e) { const bool tk = v[e] > bv; bv = tk ? v[e] : bv; bi = tk ? e : bi; }
;                 tv[r] = bv; ti[r] = bi;
; #pragma unroll
;                 for (int e = 0; e < 32; ++e) v[e] = (e == bi) ? -INFINITY : v[e]; }
;             float ev[4], es = 0.f;
; #pragma unroll
;             for (int r = 0; r < 4; ++r) { ev[r] = expf(tv[r] - tv[0]); es += ev[r]; }
;             const float rowscale = ((const float*)(F.ws + WS_HS))[row];
;             int lp[4];
; #pragma unroll
;             for (int r = 0; r < 4; ++r) lp[r] = __hip_atomic_fetch_add((LAS int*)(F.lds + 16384) + ti[r], 1, __ATOMIC_RELAXED, __HIP_MEMORY_SCOPE_WORKGROUP);
;             LDS_WAIT();
;             int base = 0;
;             if (lane < 32) { const int c = lc[lane]; unsigned* cnt = (unsigned*)(F.ws + WS_CTL) + CW_CNT + l * NE; base = c > 0 ? (int)atomicAdd(cnt + lane, (unsigned)c) : 0; }
	s_nop 1
	v_cndmask_b32_e64 v52, v237, v52, s[48:49]
	v_cmp_ne_u32_e64 s[48:49], 29, v22
	s_nop 1
	v_cndmask_b32_e64 v53, v237, v53, s[48:49]
	v_cmp_ne_u32_e64 s[48:49], 30, v22
	s_nop 1
	v_cndmask_b32_e64 v55, v237, v55, s[48:49]
	v_cmp_ne_u32_e64 s[48:49], 31, v22
	s_nop 1
	v_cndmask_b32_e64 v35, v237, v29, s[48:49]
	v_cmp_gt_f32_e64 s[48:49], v46, v24
	s_nop 1
	v_cndmask_b32_e64 v24, v24, v46, s[48:49]
	v_cndmask_b32_e64 v32, 0, 1, s[48:49]
	v_cmp_gt_f32_e64 s[48:49], v40, v24
	s_nop 1
	v_cndmask_b32_e64 v24, v24, v40, s[48:49]
	v_cndmask_b32_e64 v32, v32, 2, s[48:49]
	v_cmp_gt_f32_e64 s[48:49], v41, v24
	s_nop 1
	v_cndmask_b32_e64 v24, v24, v41, s[48:49]
	v_cndmask_b32_e64 v32, v32, 3, s[48:49]
	v_cmp_gt_f32_e64 s[48:49], v42, v24
	s_nop 1
	v_cndmask_b32_e64 v24, v24, v42, s[48:49]
	v_cndmask_b32_e64 v32, v32, 4, s[48:49]
	v_cmp_gt_f32_e64 s[48:49], v43, v24
	s_nop 1
	v_cndmask_b32_e64 v24, v24, v43, s[48:49]
	v_cndmask_b32_e64 v32, v32, 5, s[48:49]
	v_cmp_gt_f32_e64 s[48:49], v44, v24
	s_nop 1
	v_cndmask_b32_e64 v24, v24, v44, s[48:49]
	v_cndmask_b32_e64 v32, v32, 6, s[48:49]
	v_cmp_gt_f32_e64 s[48:49], v45, v24
	s_nop 1
	v_cndmask_b32_e64 v24, v24, v45, s[48:49]
	v_cndmask_b32_e64 v32, v32, 7, s[48:49]
	v_cmp_gt_f32_e64 s[48:49], v56, v24
	s_nop 1
	v_cndmask_b32_e64 v40, v32, 8, s[48:49]
	v_or_b32_e32 v32, s3, v1
	v_ashrrev_i32_e32 v33, 31, v32
	v_lshl_add_u64 v[36:37], v[32:33], 2, s[54:55]
	global_load_dword v36, v[36:37], off
	v_cndmask_b32_e64 v24, v24, v56, s[48:49]
	v_cmp_gt_f32_e64 s[48:49], v47, v24
	s_nop 1
	v_cndmask_b32_e64 v24, v24, v47, s[48:49]
	v_cndmask_b32_e64 v33, v40, 9, s[48:49]
	v_cmp_gt_f32_e64 s[48:49], v26, v24
	s_nop 1
	v_cndmask_b32_e64 v24, v24, v26, s[48:49]
	v_cndmask_b32_e64 v33, v33, 10, s[48:49]
	v_cmp_gt_f32_e64 s[48:49], v54, v24
	s_nop 1
	v_cndmask_b32_e64 v24, v24, v54, s[48:49]
	v_cndmask_b32_e64 v26, v33, 11, s[48:49]
	v_cmp_gt_f32_e64 s[48:49], v28, v24
	s_nop 1
	v_cndmask_b32_e64 v24, v24, v28, s[48:49]
	v_cndmask_b32_e64 v26, v26, 12, s[48:49]
	v_cmp_gt_f32_e64 s[48:49], v57, v24
	s_nop 1
	v_cndmask_b32_e64 v24, v24, v57, s[48:49]
	v_cndmask_b32_e64 v26, v26, 13, s[48:49]
	v_cmp_gt_f32_e64 s[48:49], v30, v24
	s_nop 1
	v_cndmask_b32_e64 v24, v24, v30, s[48:49]
	v_cndmask_b32_e64 v26, v26, 14, s[48:49]
	v_cmp_gt_f32_e64 s[48:49], v58, v24
	s_nop 1
	v_cndmask_b32_e64 v24, v24, v58, s[48:49]
	v_cndmask_b32_e64 v26, v26, 15, s[48:49]
	v_cmp_gt_f32_e64 s[48:49], v59, v24
	s_nop 1
	v_cndmask_b32_e64 v24, v24, v59, s[48:49]
	v_cndmask_b32_e64 v26, v26, 16, s[48:49]
	v_cmp_gt_f32_e64 s[48:49], v60, v24
	s_nop 1
	v_cndmask_b32_e64 v24, v24, v60, s[48:49]
	v_cndmask_b32_e64 v26, v26, 17, s[48:49]
	v_cmp_gt_f32_e64 s[48:49], v34, v24
	s_nop 1
	v_cndmask_b32_e64 v24, v24, v34, s[48:49]
	v_cndmask_b32_e64 v26, v26, 18, s[48:49]
	v_cmp_gt_f32_e64 s[48:49], v61, v24
	s_nop 1
	v_cndmask_b32_e64 v24, v24, v61, s[48:49]
	v_cndmask_b32_e64 v26, v26, 19, s[48:49]
	v_cmp_gt_f32_e64 s[48:49], v62, v24
	s_nop 1
	v_cndmask_b32_e64 v24, v24, v62, s[48:49]
	v_cndmask_b32_e64 v26, v26, 20, s[48:49]
	v_cmp_gt_f32_e64 s[48:49], v63, v24
	s_nop 1
	v_cndmask_b32_e64 v24, v24, v63, s[48:49]
	v_cndmask_b32_e64 v26, v26, 21, s[48:49]
	v_cmp_gt_f32_e64 s[48:49], v38, v24
	s_nop 1
	v_cndmask_b32_e64 v24, v24, v38, s[48:49]
	v_cndmask_b32_e64 v26, v26, 22, s[48:49]
	v_cmp_gt_f32_e64 s[48:49], v39, v24
	s_nop 1
	v_cndmask_b32_e64 v24, v24, v39, s[48:49]
	v_cndmask_b32_e64 v26, v26, 23, s[48:49]
	v_cmp_gt_f32_e64 s[48:49], v48, v24
	s_nop 1
	v_cndmask_b32_e64 v24, v24, v48, s[48:49]
	v_cndmask_b32_e64 v26, v26, 24, s[48:49]
	v_cmp_gt_f32_e64 s[48:49], v49, v24
	s_nop 1
	v_cndmask_b32_e64 v24, v24, v49, s[48:49]
	v_cndmask_b32_e64 v26, v26, 25, s[48:49]
	v_cmp_gt_f32_e64 s[48:49], v50, v24
	s_nop 1
	v_cndmask_b32_e64 v24, v24, v50, s[48:49]
	v_cndmask_b32_e64 v26, v26, 26, s[48:49]
	v_cmp_gt_f32_e64 s[48:49], v51, v24
	s_nop 1
	v_cndmask_b32_e64 v24, v24, v51, s[48:49]
	v_cndmask_b32_e64 v26, v26, 27, s[48:49]
	v_cmp_gt_f32_e64 s[48:49], v52, v24
	s_nop 1
	v_cndmask_b32_e64 v24, v24, v52, s[48:49]
	v_cndmask_b32_e64 v26, v26, 28, s[48:49]
	v_cmp_gt_f32_e64 s[48:49], v53, v24
	s_nop 1
	v_cndmask_b32_e64 v24, v24, v53, s[48:49]
	v_cndmask_b32_e64 v26, v26, 29, s[48:49]
	v_cmp_gt_f32_e64 s[48:49], v55, v24
	s_nop 1
	v_cndmask_b32_e64 v33, v24, v55, s[48:49]
	v_cndmask_b32_e64 v26, v26, 30, s[48:49]
	v_cmp_gt_f32_e64 s[48:49], v35, v33
	s_nop 1
	v_cndmask_b32_e64 v24, v26, 31, s[48:49]
	v_lshl_add_u32 v26, v18, 2, 0
	ds_add_rtn_u32 v34, v26, v222 offset:16384
	v_lshl_add_u32 v26, v20, 2, 0
	ds_add_rtn_u32 v30, v26, v222 offset:16384
	v_lshl_add_u32 v26, v22, 2, 0
	ds_add_rtn_u32 v28, v26, v222 offset:16384
	v_lshl_add_u32 v26, v24, 2, 0
	ds_add_rtn_u32 v26, v26, v222 offset:16384
	s_waitcnt lgkmcnt(0)
	s_and_saveexec_b64 s[4:5], s[40:41]
	s_cbranch_execz .LBB0_2133
	ds_read_b32 v37, v157 offset:16384
	v_mov_b32_e32 v25, 0
	s_waitcnt lgkmcnt(0)
	v_cmp_lt_i32_e64 s[50:51], 0, v37
	s_and_saveexec_b64 s[6:7], s[50:51]
	s_cbranch_execz .LBB0_2132
	global_atomic_add v25, v[122:123], v37, off sc0
	s_branch .LBB0_2132
